# v56 + attn_step row-sum kept as per-lane partial (l = l*alpha + ps) in MLA / NSA selected / NSA window loops: per-tile ds_bpermute + wait removed, one xor-32 exchange per item before l is used
# speedup vs baseline: 1.0008x; 1.0008x over previous
; DI unsigned pack2(float a, float b) { f32x2_t v = {a, b}; bf16x2_t r = __builtin_convertvector(v, bf16x2_t); return __builtin_bit_cast(unsigned, r); }
; DI float bflo(unsigned u) { return __uint_as_float(u << 16); }
; DI float bfhi(unsigned u) { return __uint_as_float(u & 0xffff0000u); }
; DI float siluf_(float x) { return x * __builtin_amdgcn_rcpf(1.f + __expf(-x)); }
; DI void attn_write_staged(const f32x16& o0, const f32x16& o1, bf16_t* og, const bf16_t* z, size_t tok0, int head, int lane, bf16_t* wl) {
;   const int q = lane & 31, h = lane >> 5;
; #pragma unroll
;   for (int dt = 0; dt < 2; ++dt)
; #pragma unroll
;     for (int q4 = 0; q4 < 4; ++q4) {
;       const f32x16& o = dt ? o1 : o0;
;       *(uint2*)(wl + q * 72 + dt * 32 + 8 * q4 + 4 * h) = make_uint2(pack2(o[4 * q4], o[4 * q4 + 1]), pack2(o[4 * q4 + 2], o[4 * q4 + 3]));
;     }
; #pragma unroll
;   for (int k = 0; k < 4; ++k) {
;     const int ci = lane + 64 * k, row = ci >> 3, c8 = ci & 7;
;     const u32x4 ov = *(const u32x4*)(wl + row * 72 + c8 * 8);
;     const size_t off = (tok0 + row) * 1024 + head * 64 + c8 * 8;
;     const u32x4 zv = ldg16(z + off);
;     u32x4 r;
;     r.x = pack2(bflo(ov.x) * siluf_(bflo(zv.x)), bfhi(ov.x) * siluf_(bfhi(zv.x)));
;     r.y = pack2(bflo(ov.y) * siluf_(bflo(zv.y)), bfhi(ov.y) * siluf_(bfhi(zv.y)));
;     r.z = pack2(bflo(ov.z) * siluf_(bflo(zv.z)), bfhi(ov.z) * siluf_(bfhi(zv.z)));
;     r.w = pack2(bflo(ov.w) * siluf_(bflo(zv.w)), bfhi(ov.w) * siluf_(bfhi(zv.w)));
;     *(u32x4*)(og + off) = r;
;   }
; DI void phase_attn_mla(const Params& P, bf16_t* og, unsigned char* smem, int L, int G) {
;     ...
;     const float il = 1.f / l;
; #pragma unroll
;     for (int q = 0; q < 16; ++q) { o0[q] *= il; o1[q] *= il; }
;     attn_write_staged(o0, o1, og, big + ML_Z, (size_t)b * SEQ + t0, head, lane, (bf16_t*)(smem + 49152) + w * (32 * 72));
.LBB0_771:
	v_ashrrev_i32_e32 v163, 31, v162
	v_lshl_add_u64 v[2:3], s[20:21], 0, v[162:163]
	v_or_b32_e32 v0, s18, v138
	v_or_b32_e32 v4, v2, v146
	v_mov_b32_e32 v5, v3
	v_lshlrev_b64 v[48:49], 11, v[4:5]
	v_lshlrev_b32_e32 v50, 1, v0
	v_or_b32_e32 v48, v48, v50
	v_lshl_add_u64 v[4:5], s[10:11], 0, v[48:49]
	v_mov_b32_e32 v254, 0x4000
	v_mov_b32_e32 v255, 0
	v_lshl_add_u64 v[248:249], v[4:5], 0, v[254:255]
	v_lshl_add_u64 v[250:251], v[248:249], 0, v[254:255]
	v_lshl_add_u64 v[252:253], v[250:251], 0, v[254:255]
	global_load_dwordx4 v[4:7], v[4:5], off
	global_load_dwordx4 v[116:119], v[248:249], off
	global_load_dwordx4 v[120:123], v[250:251], off
	global_load_dwordx4 v[124:127], v[252:253], off
	v_lshlrev_b32_e32 v8, 2, v183
	ds_bpermute_b32 v9, v8, v165
	s_waitcnt lgkmcnt(0)
	v_add_f32_e32 v165, v165, v9
	v_div_scale_f32 v0, s[18:19], v165, v165, 1.0
	v_rcp_f32_e32 v8, v0
	v_div_scale_f32 v9, vcc, 1.0, v165, 1.0
	v_add_u32_e32 v51, 0xc000, v177
	v_fma_f32 v10, -v0, v8, 1.0
	v_fmac_f32_e32 v8, v10, v8
	v_mul_f32_e32 v10, v9, v8
	v_fma_f32 v11, -v0, v10, v9
	v_fmac_f32_e32 v10, v11, v8
	v_fma_f32 v0, -v0, v10, v9
	v_div_fmas_f32 v0, v0, v8, v10
	v_div_fixup_f32 v0, v0, v165, 1.0
	v_pk_mul_f32 v[8:9], v[32:33], v[0:1] op_sel_hi:[1,0]
	v_pk_mul_f32 v[10:11], v[16:17], v[0:1] op_sel_hi:[1,0]
	v_pk_mul_f32 v[12:13], v[34:35], v[0:1] op_sel_hi:[1,0]
	v_pk_mul_f32 v[14:15], v[18:19], v[0:1] op_sel_hi:[1,0]
	v_pk_mul_f32 v[16:17], v[36:37], v[0:1] op_sel_hi:[1,0]
	v_pk_mul_f32 v[18:19], v[20:21], v[0:1] op_sel_hi:[1,0]
	v_pk_mul_f32 v[20:21], v[38:39], v[0:1] op_sel_hi:[1,0]
	v_pk_mul_f32 v[24:25], v[24:25], v[0:1] op_sel_hi:[1,0]
	v_pk_mul_f32 v[26:27], v[26:27], v[0:1] op_sel_hi:[1,0]
	v_pk_mul_f32 v[22:23], v[22:23], v[0:1] op_sel_hi:[1,0]
	v_pk_mul_f32 v[32:33], v[40:41], v[0:1] op_sel_hi:[1,0]
	v_pk_mul_f32 v[34:35], v[42:43], v[0:1] op_sel_hi:[1,0]
	v_pk_mul_f32 v[36:37], v[44:45], v[0:1] op_sel_hi:[1,0]
	v_pk_mul_f32 v[28:29], v[28:29], v[0:1] op_sel_hi:[1,0]
	v_pk_mul_f32 v[38:39], v[46:47], v[0:1] op_sel_hi:[1,0]
	v_pk_mul_f32 v[30:31], v[30:31], v[0:1] op_sel_hi:[1,0]
	v_cvt_pk_bf16_f32 v8, v8, v9
	v_cvt_pk_bf16_f32 v9, v12, v13
	v_cvt_pk_bf16_f32 v12, v16, v17
	v_cvt_pk_bf16_f32 v13, v20, v21
	v_cvt_pk_bf16_f32 v10, v10, v11
	v_cvt_pk_bf16_f32 v11, v14, v15
	v_cvt_pk_bf16_f32 v14, v18, v19
	v_cvt_pk_bf16_f32 v18, v24, v25
	v_cvt_pk_bf16_f32 v19, v26, v27
	v_cvt_pk_bf16_f32 v16, v32, v33
	v_cvt_pk_bf16_f32 v17, v34, v35
	v_cvt_pk_bf16_f32 v20, v36, v37
	v_cvt_pk_bf16_f32 v21, v38, v39
	v_cvt_pk_bf16_f32 v15, v22, v23
	v_cvt_pk_bf16_f32 v22, v28, v29
	v_cvt_pk_bf16_f32 v23, v30, v31
	ds_write2_b64 v51, v[8:9], v[12:13] offset1:2
	ds_write2_b64 v51, v[16:17], v[20:21] offset0:4 offset1:6
	ds_write2_b64 v51, v[10:11], v[14:15] offset0:8 offset1:10
	ds_write2_b64 v51, v[18:19], v[22:23] offset0:12 offset1:14
	ds_read_b128 v[8:11], v181 offset:49152
	ds_read_b128 v[12:15], v181 offset:50304
	s_add_i32 s38, s38, s74
	s_cmpk_gt_i32 s38, 0xfff
	s_waitcnt lgkmcnt(1)
	v_lshlrev_b32_e32 v16, 16, v8
	v_and_b32_e32 v17, 0xffff0000, v8
	v_lshlrev_b32_e32 v8, 16, v9
	v_and_b32_e32 v9, 0xffff0000, v9
	s_waitcnt vmcnt(3)
	v_lshlrev_b32_e32 v18, 16, v4
	v_and_b32_e32 v19, 0xffff0000, v4
	v_lshlrev_b32_e32 v4, 16, v5
	v_and_b32_e32 v5, 0xffff0000, v5
	v_lshlrev_b32_e32 v20, 16, v6
	v_and_b32_e32 v21, 0xffff0000, v6
	v_mul_f32_e32 v0, 0xbfb8aa3b, v18
	v_mul_f32_e32 v6, 0xbfb8aa3b, v19
	v_mul_f32_e32 v22, 0xbfb8aa3b, v4
	v_mul_f32_e32 v23, 0xbfb8aa3b, v5
	v_exp_f32_e32 v0, v0
	v_exp_f32_e32 v6, v6
	v_exp_f32_e32 v22, v22
	v_exp_f32_e32 v23, v23
	v_mul_f32_e32 v24, 0xbfb8aa3b, v20
	v_mul_f32_e32 v25, 0xbfb8aa3b, v21
	v_add_f32_e32 v0, 1.0, v0
	v_add_f32_e32 v6, 1.0, v6
	v_exp_f32_e32 v26, v24
	v_exp_f32_e32 v27, v25
	v_add_f32_e32 v24, 1.0, v22
	v_add_f32_e32 v25, 1.0, v23
	v_rcp_f32_e32 v22, v0
	v_rcp_f32_e32 v23, v6
	v_rcp_f32_e32 v24, v24
	v_rcp_f32_e32 v25, v25
	v_add_f32_e32 v0, 1.0, v26
	v_pk_mul_f32 v[18:19], v[22:23], v[18:19]
	v_rcp_f32_e32 v26, v0
	v_pk_mul_f32 v[16:17], v[18:19], v[16:17]
	v_add_f32_e32 v0, 1.0, v27
	v_lshlrev_b32_e32 v18, 16, v7
	v_pk_mul_f32 v[4:5], v[24:25], v[4:5]
	v_rcp_f32_e32 v27, v0
	v_and_b32_e32 v19, 0xffff0000, v7
	v_mul_f32_e32 v0, 0xbfb8aa3b, v18
	v_pk_mul_f32 v[8:9], v[4:5], v[8:9]
	v_exp_f32_e32 v0, v0
	v_mul_f32_e32 v6, 0xbfb8aa3b, v19
	v_cvt_pk_bf16_f32 v5, v8, v9
	v_lshlrev_b32_e32 v8, 16, v10
	v_and_b32_e32 v9, 0xffff0000, v10
	v_exp_f32_e32 v10, v6
	v_cvt_pk_bf16_f32 v4, v16, v17
	v_pk_mul_f32 v[16:17], v[26:27], v[20:21]
	v_add_f32_e32 v0, 1.0, v0
	v_pk_mul_f32 v[6:7], v[16:17], v[8:9]
	v_rcp_f32_e32 v8, v0
	v_add_f32_e32 v0, 1.0, v10
	v_rcp_f32_e32 v9, v0
	v_lshlrev_b32_e32 v10, 16, v11
	v_and_b32_e32 v11, 0xffff0000, v11
	v_cvt_pk_bf16_f32 v6, v6, v7
	v_pk_mul_f32 v[8:9], v[8:9], v[18:19]
	s_waitcnt lgkmcnt(0)
	v_lshlrev_b32_e32 v18, 16, v14
	v_pk_mul_f32 v[8:9], v[8:9], v[10:11]
	v_or_b32_e32 v10, v2, v150
	v_cvt_pk_bf16_f32 v7, v8, v9
	v_lshl_add_u64 v[8:9], s[94:95], 0, v[48:49]
	global_store_dwordx4 v[8:9], v[4:7], off
	v_mov_b32_e32 v11, v3
	v_lshlrev_b64 v[16:17], 11, v[10:11]
	v_or_b32_e32 v4, v2, v148
	v_mov_b32_e32 v5, v3
	v_lshlrev_b64 v[8:9], 11, v[4:5]
	v_or_b32_e32 v8, v8, v50
	v_lshl_add_u64 v[4:5], s[10:11], 0, v[8:9]
	v_lshlrev_b32_e32 v10, 16, v12
	v_and_b32_e32 v11, 0xffff0000, v12
	v_lshlrev_b32_e32 v12, 16, v13
	v_and_b32_e32 v13, 0xffff0000, v13
	v_and_b32_e32 v19, 0xffff0000, v14
	v_lshlrev_b32_e32 v14, 16, v15
	v_and_b32_e32 v15, 0xffff0000, v15
	v_lshl_add_u64 v[8:9], s[94:95], 0, v[8:9]
	v_or_b32_e32 v16, v16, v50
	v_or_b32_e32 v2, v2, v152
	s_waitcnt vmcnt(3)
; DI unsigned pack2(float a, float b) { f32x2_t v = {a, b}; bf16x2_t r = __builtin_convertvector(v, bf16x2_t); return __builtin_bit_cast(unsigned, r); }
; DI float bflo(unsigned u) { return __uint_as_float(u << 16); }
; DI float bfhi(unsigned u) { return __uint_as_float(u & 0xffff0000u); }
; DI float siluf_(float x) { return x * __builtin_amdgcn_rcpf(1.f + __expf(-x)); }
; DI void attn_write_staged(const f32x16& o0, const f32x16& o1, bf16_t* og, const bf16_t* z, size_t tok0, int head, int lane, bf16_t* wl) {
;     ...
; #pragma unroll
;   for (int k = 0; k < 4; ++k) {
;     const int ci = lane + 64 * k, row = ci >> 3, c8 = ci & 7;
;     const u32x4 ov = *(const u32x4*)(wl + row * 72 + c8 * 8);
;     const size_t off = (tok0 + row) * 1024 + head * 64 + c8 * 8;
;     const u32x4 zv = ldg16(z + off);
;     u32x4 r;
;     r.x = pack2(bflo(ov.x) * siluf_(bflo(zv.x)), bfhi(ov.x) * siluf_(bfhi(zv.x)));
;     r.y = pack2(bflo(ov.y) * siluf_(bflo(zv.y)), bfhi(ov.y) * siluf_(bfhi(zv.y)));
;     r.z = pack2(bflo(ov.z) * siluf_(bflo(zv.z)), bfhi(ov.z) * siluf_(bfhi(zv.z)));
;     r.w = pack2(bflo(ov.w) * siluf_(bflo(zv.w)), bfhi(ov.w) * siluf_(bfhi(zv.w)));
;     *(u32x4*)(og + off) = r;
;   }
	v_mov_b32_e32 v4, v116
	v_mov_b32_e32 v5, v117
	v_mov_b32_e32 v6, v118
	v_mov_b32_e32 v7, v119
	v_lshlrev_b32_e32 v20, 16, v4
	v_and_b32_e32 v21, 0xffff0000, v4
	v_lshlrev_b32_e32 v4, 16, v5
	v_and_b32_e32 v5, 0xffff0000, v5
	v_lshlrev_b32_e32 v22, 16, v6
	v_and_b32_e32 v23, 0xffff0000, v6
	v_lshlrev_b32_e32 v6, 16, v7
	v_and_b32_e32 v7, 0xffff0000, v7
	v_mul_f32_e32 v0, 0xbfb8aa3b, v20
	v_mul_f32_e32 v24, 0xbfb8aa3b, v21
	v_mul_f32_e32 v25, 0xbfb8aa3b, v4
	v_mul_f32_e32 v26, 0xbfb8aa3b, v5
	v_mul_f32_e32 v27, 0xbfb8aa3b, v22
	v_mul_f32_e32 v28, 0xbfb8aa3b, v23
	v_mul_f32_e32 v29, 0xbfb8aa3b, v6
	v_mul_f32_e32 v30, 0xbfb8aa3b, v7
	v_exp_f32_e32 v0, v0
	v_exp_f32_e32 v24, v24
	v_exp_f32_e32 v25, v25
	v_exp_f32_e32 v26, v26
	v_exp_f32_e32 v27, v27
	v_exp_f32_e32 v28, v28
	v_exp_f32_e32 v29, v29
	v_exp_f32_e32 v30, v30
	v_add_f32_e32 v0, 1.0, v0
	v_add_f32_e32 v31, 1.0, v24
	v_add_f32_e32 v32, 1.0, v25
	v_add_f32_e32 v33, 1.0, v26
	v_add_f32_e32 v34, 1.0, v27
	v_add_f32_e32 v35, 1.0, v28
	v_add_f32_e32 v36, 1.0, v29
	v_add_f32_e32 v37, 1.0, v30
	v_rcp_f32_e32 v24, v0
	v_rcp_f32_e32 v25, v31
	v_rcp_f32_e32 v26, v32
	v_rcp_f32_e32 v27, v33
	v_rcp_f32_e32 v28, v34
	v_rcp_f32_e32 v29, v35
	v_rcp_f32_e32 v30, v36
	v_rcp_f32_e32 v31, v37
	v_pk_mul_f32 v[20:21], v[24:25], v[20:21]
	v_pk_mul_f32 v[4:5], v[26:27], v[4:5]
	v_pk_mul_f32 v[22:23], v[28:29], v[22:23]
	v_pk_mul_f32 v[6:7], v[30:31], v[6:7]
	v_pk_mul_f32 v[10:11], v[20:21], v[10:11]
	v_pk_mul_f32 v[12:13], v[4:5], v[12:13]
	v_pk_mul_f32 v[18:19], v[22:23], v[18:19]
	v_pk_mul_f32 v[14:15], v[6:7], v[14:15]
	v_cvt_pk_bf16_f32 v4, v10, v11
	v_cvt_pk_bf16_f32 v5, v12, v13
	v_cvt_pk_bf16_f32 v6, v18, v19
	v_cvt_pk_bf16_f32 v7, v14, v15
	global_store_dwordx4 v[8:9], v[4:7], off
	ds_read_b128 v[8:11], v181 offset:51456
	ds_read_b128 v[12:15], v181 offset:52608
	v_lshl_add_u64 v[4:5], s[10:11], 0, v[16:17]
	v_lshlrev_b64 v[18:19], 11, v[2:3]
	s_waitcnt lgkmcnt(1)
	v_lshlrev_b32_e32 v2, 16, v8
	v_and_b32_e32 v3, 0xffff0000, v8
	v_lshlrev_b32_e32 v8, 16, v9
	v_and_b32_e32 v9, 0xffff0000, v9
	v_lshlrev_b32_e32 v22, 16, v10
	v_and_b32_e32 v23, 0xffff0000, v10
	v_lshlrev_b32_e32 v10, 16, v11
	v_and_b32_e32 v11, 0xffff0000, v11
	v_or_b32_e32 v18, v18, v50
	v_lshl_add_u64 v[16:17], s[94:95], 0, v[16:17]
	v_lshl_add_u64 v[20:21], s[10:11], 0, v[18:19]
	s_waitcnt vmcnt(3)
	v_mov_b32_e32 v4, v120
	v_mov_b32_e32 v5, v121
	v_mov_b32_e32 v6, v122
	v_mov_b32_e32 v7, v123
	v_lshlrev_b32_e32 v24, 16, v4
	v_and_b32_e32 v25, 0xffff0000, v4
	v_lshlrev_b32_e32 v4, 16, v5
	v_and_b32_e32 v5, 0xffff0000, v5
	v_lshlrev_b32_e32 v26, 16, v6
	v_and_b32_e32 v27, 0xffff0000, v6
	v_lshlrev_b32_e32 v6, 16, v7
	v_and_b32_e32 v7, 0xffff0000, v7
	v_mul_f32_e32 v0, 0xbfb8aa3b, v24
	v_mul_f32_e32 v28, 0xbfb8aa3b, v25
	v_mul_f32_e32 v29, 0xbfb8aa3b, v4
	v_mul_f32_e32 v30, 0xbfb8aa3b, v5
	v_mul_f32_e32 v31, 0xbfb8aa3b, v26
	v_mul_f32_e32 v32, 0xbfb8aa3b, v27
	v_mul_f32_e32 v33, 0xbfb8aa3b, v6
	v_mul_f32_e32 v34, 0xbfb8aa3b, v7
	v_exp_f32_e32 v0, v0
	v_exp_f32_e32 v28, v28
	v_exp_f32_e32 v29, v29
	v_exp_f32_e32 v30, v30
	v_exp_f32_e32 v31, v31
	v_exp_f32_e32 v32, v32
	v_exp_f32_e32 v33, v33
	v_exp_f32_e32 v34, v34
	v_add_f32_e32 v0, 1.0, v0
	v_add_f32_e32 v35, 1.0, v28
	v_add_f32_e32 v36, 1.0, v29
	v_add_f32_e32 v37, 1.0, v30
	v_add_f32_e32 v38, 1.0, v31
	v_add_f32_e32 v39, 1.0, v32
	v_add_f32_e32 v40, 1.0, v33
	v_add_f32_e32 v41, 1.0, v34
	v_rcp_f32_e32 v28, v0
	v_rcp_f32_e32 v29, v35
	v_rcp_f32_e32 v30, v36
	v_rcp_f32_e32 v31, v37
	v_rcp_f32_e32 v32, v38
	v_rcp_f32_e32 v33, v39
	v_rcp_f32_e32 v34, v40
	v_rcp_f32_e32 v35, v41
	v_pk_mul_f32 v[24:25], v[28:29], v[24:25]
	v_pk_mul_f32 v[4:5], v[30:31], v[4:5]
	v_pk_mul_f32 v[26:27], v[32:33], v[26:27]
	v_pk_mul_f32 v[6:7], v[34:35], v[6:7]
	v_pk_mul_f32 v[2:3], v[24:25], v[2:3]
	v_pk_mul_f32 v[4:5], v[4:5], v[8:9]
	v_pk_mul_f32 v[8:9], v[26:27], v[22:23]
	v_pk_mul_f32 v[6:7], v[6:7], v[10:11]
	v_cvt_pk_bf16_f32 v2, v2, v3
	v_cvt_pk_bf16_f32 v3, v4, v5
	v_cvt_pk_bf16_f32 v4, v8, v9
	v_cvt_pk_bf16_f32 v5, v6, v7
	global_store_dwordx4 v[16:17], v[2:5], off
	v_lshl_add_u64 v[6:7], s[94:95], 0, v[18:19]
	s_waitcnt lgkmcnt(0)
	v_lshlrev_b32_e32 v8, 16, v12
	v_and_b32_e32 v9, 0xffff0000, v12
	v_lshlrev_b32_e32 v10, 16, v13
	v_and_b32_e32 v11, 0xffff0000, v13
	v_lshlrev_b32_e32 v12, 16, v14
	v_and_b32_e32 v13, 0xffff0000, v14
	v_lshlrev_b32_e32 v14, 16, v15
	v_and_b32_e32 v15, 0xffff0000, v15
	s_waitcnt vmcnt(3)
	v_mov_b32_e32 v2, v124
	v_mov_b32_e32 v3, v125
	v_mov_b32_e32 v4, v126
	v_mov_b32_e32 v5, v127
	v_lshlrev_b32_e32 v16, 16, v2
	v_and_b32_e32 v17, 0xffff0000, v2
	v_lshlrev_b32_e32 v2, 16, v3
	v_and_b32_e32 v3, 0xffff0000, v3
	v_lshlrev_b32_e32 v18, 16, v4
	v_and_b32_e32 v19, 0xffff0000, v4
	v_lshlrev_b32_e32 v4, 16, v5
	v_and_b32_e32 v5, 0xffff0000, v5
	v_mul_f32_e32 v0, 0xbfb8aa3b, v16
	v_mul_f32_e32 v20, 0xbfb8aa3b, v17
	v_mul_f32_e32 v21, 0xbfb8aa3b, v2
	v_mul_f32_e32 v22, 0xbfb8aa3b, v3
	v_mul_f32_e32 v23, 0xbfb8aa3b, v18
	v_mul_f32_e32 v24, 0xbfb8aa3b, v19
	v_mul_f32_e32 v25, 0xbfb8aa3b, v4
	v_mul_f32_e32 v26, 0xbfb8aa3b, v5
	v_exp_f32_e32 v0, v0
	v_exp_f32_e32 v20, v20
	v_exp_f32_e32 v21, v21
	v_exp_f32_e32 v22, v22
	v_exp_f32_e32 v23, v23
	v_exp_f32_e32 v24, v24
	v_exp_f32_e32 v25, v25
	v_exp_f32_e32 v26, v26
	v_add_f32_e32 v0, 1.0, v0
	v_add_f32_e32 v27, 1.0, v20
	v_add_f32_e32 v28, 1.0, v21
	v_add_f32_e32 v29, 1.0, v22
	v_add_f32_e32 v30, 1.0, v23
	v_add_f32_e32 v31, 1.0, v24
	v_add_f32_e32 v32, 1.0, v25
	v_add_f32_e32 v33, 1.0, v26
	v_rcp_f32_e32 v20, v0
	v_rcp_f32_e32 v21, v27
	v_rcp_f32_e32 v22, v28
	v_rcp_f32_e32 v23, v29
	v_rcp_f32_e32 v24, v30
	v_rcp_f32_e32 v25, v31
	v_rcp_f32_e32 v26, v32
	v_rcp_f32_e32 v27, v33
	v_pk_mul_f32 v[16:17], v[20:21], v[16:17]
	v_pk_mul_f32 v[2:3], v[22:23], v[2:3]
	v_pk_mul_f32 v[18:19], v[24:25], v[18:19]
	v_pk_mul_f32 v[4:5], v[26:27], v[4:5]
	v_pk_mul_f32 v[8:9], v[16:17], v[8:9]
	v_pk_mul_f32 v[10:11], v[2:3], v[10:11]
	v_pk_mul_f32 v[12:13], v[18:19], v[12:13]
	v_pk_mul_f32 v[14:15], v[4:5], v[14:15]
	v_cvt_pk_bf16_f32 v2, v8, v9
	v_cvt_pk_bf16_f32 v3, v10, v11
	v_cvt_pk_bf16_f32 v4, v12, v13
	v_cvt_pk_bf16_f32 v5, v14, v15
	global_store_dwordx4 v[6:7], v[2:5], off
	s_cbranch_scc1 .LBB0_793

; template <int DQK, bool MASKED, int MODE, class MF>
; DI void attn_step(const bf16_t* sK, const bf16_t* sVt, const bf16x8 (&qf)[DQK / 16], f32x16& o0, f32x16& o1, float& m, float& l,
;                   float sc, const MF& mf, int lane, f32x16 (&s)[2], float invl, bool lanevalid = true) {
;   const int r = lane & 31, h = lane >> 5;
;   const int pr = kperm(r);
;   constexpr int KST = DQK + 8;
;   bf16x8 kf[2][DQK / 16];
; #pragma unroll
;   for (int sub = 0; sub < 2; ++sub)
; #pragma unroll
;     for (int ks = 0; ks < DQK / 16; ++ks) kf[sub][ks] = *(const bf16x8*)(sK + (sub * 32 + pr) * KST + ks * 16 + 8 * h);
;   __builtin_amdgcn_sched_barrier(0);
; #pragma unroll
;   for (int q = 0; q < 16; ++q) { s[0][q] = 0.f; s[1][q] = 0.f; }
; #pragma unroll
;   for (int ks = 0; ks < DQK / 16; ++ks) {
;     s[0] = MFMA(kf[0][ks], qf[ks], s[0]);
;     s[1] = MFMA(kf[1][ks], qf[ks], s[1]);
;   }
;   bf16x8 vf[2][2][2];
;   if (MODE != 1) {
; #pragma unroll
;     for (int sub = 0; sub < 2; ++sub)
; #pragma unroll
;       for (int s2 = 0; s2 < 2; ++s2) {
;         vf[sub][s2][0] = *(const bf16x8*)(sVt + r * 72 + sub * 32 + s2 * 16 + 8 * h);
;         vf[sub][s2][1] = *(const bf16x8*)(sVt + (32 + r) * 72 + sub * 32 + s2 * 16 + 8 * h);
;       }
;     __builtin_amdgcn_sched_barrier(0);
;   }
;   float mxr = -3.0e38f;
; #pragma unroll
;   for (int sub = 0; sub < 2; ++sub)
; #pragma unroll
;     for (int q = 0; q < 16; ++q) {
;       if (MASKED) { const int kk = sub * 32 + 16 * (q >> 3) + 8 * h + (q & 7); s[sub][q] = mf(kk) ? s[sub][q] : -3.0e38f; }
;       if (MODE != 2) mxr = fmaxf(mxr, s[sub][q]);
;     }
;   float alpha = 1.f;
;   if (MODE != 2) {
;     float mx = fmaxf(m, mxr * sc);
;     mx = fmaxf(mx, shx(mx, 32));
;     if (!MASKED) mx = lanevalid ? mx : m;
;     alpha = fexp2(m - mx);
;     m = mx;
;   }
;   const float moff = (!MASKED && !lanevalid) ? 1.0e30f : m;
;   float ps = 0.f;
; #pragma unroll
;   for (int sub = 0; sub < 2; ++sub)
; #pragma unroll
;     for (int q = 0; q < 16; ++q) {
;       float pv = fexp2(__builtin_fmaf(s[sub][q], sc, -moff));
;       if (MASKED && MODE != 0) pv = (s[sub][q] > -1.0e38f) ? pv : 0.f;
;       if (MODE == 2) pv *= invl;
;       s[sub][q] = pv;
;       ps += pv;
;     }
; DI void phase_attn_mla(const Params& P, bf16_t* og, unsigned char* smem, int L, int G) {
;     ...
;       if (key0 <= t0 + 31) {
.LBB0_785:
	v_cmp_le_i32_e32 vcc, s14, v163
	s_and_saveexec_b64 s[22:23], vcc
	s_cbranch_execz .Lmy_mla_skip
	s_add_i32 s24, s14, 63
	s_mulk_i32 s40, 0x2c00
	v_cmp_le_i32_e32 vcc, s24, v162
	s_lshl_b32 s39, s40, 1
	v_max_f32_e32 v0, v186, v186
	s_and_saveexec_b64 s[24:25], vcc
	s_xor_b64 s[24:25], exec, s[24:25]
	s_cbranch_execz .LBB0_788
	v_lshl_add_u32 v14, s40, 1, v143
	ds_read_b128 v[2:5], v14
	ds_read_b128 v[6:9], v14 offset:32
	ds_read_b128 v[10:13], v14 offset:64
	ds_read_b128 v[116:119], v14 offset:96
	ds_read_b128 v[120:123], v14 offset:128
	ds_read_b128 v[124:127], v14 offset:160
	ds_read_b128 v[48:51], v14 offset:6656
	ds_read_b128 v[128:131], v14 offset:6688
	ds_read_b128 v[132:135], v14 offset:6720
	ds_read_b128 v[188:191], v14 offset:6752
	ds_read_b128 v[194:197], v14 offset:6784
	ds_read_b128 v[198:201], v14 offset:6816
	s_waitcnt lgkmcnt(11)
	v_mfma_f32_32x32x16_bf16 v[64:79], v[2:5], v[100:103], 0
	v_add3_u32 v2, s39, v172, v156
	v_add3_u32 v3, s39, v173, v156
	s_waitcnt lgkmcnt(10)
	v_mfma_f32_32x32x16_bf16 v[64:79], v[6:9], v[80:83], v[64:79]
	s_waitcnt lgkmcnt(5)
	v_mfma_f32_32x32x16_bf16 v[48:63], v[48:51], v[100:103], 0
	v_mfma_f32_32x32x16_bf16 v[64:79], v[10:13], v[84:87], v[64:79]
	s_waitcnt lgkmcnt(4)
	v_mfma_f32_32x32x16_bf16 v[48:63], v[128:131], v[80:83], v[48:63]
	v_mfma_f32_32x32x16_bf16 v[64:79], v[116:119], v[88:91], v[64:79]
	s_waitcnt lgkmcnt(3)
	v_mfma_f32_32x32x16_bf16 v[48:63], v[132:135], v[84:87], v[48:63]
	v_mfma_f32_32x32x16_bf16 v[64:79], v[120:123], v[92:95], v[64:79]
	s_waitcnt lgkmcnt(2)
	v_mfma_f32_32x32x16_bf16 v[48:63], v[188:191], v[88:91], v[48:63]
	v_mfma_f32_32x32x16_bf16 v[64:79], v[124:127], v[96:99], v[64:79]
	ds_read_b128 v[132:135], v2 offset:13312
	ds_read_b128 v[124:127], v2 offset:13344
	ds_read_b128 v[128:131], v3 offset:13312
	ds_read_b128 v[120:123], v3 offset:13344
	ds_read_b128 v[116:119], v2 offset:13376
	ds_read_b128 v[6:9], v2 offset:13408
	ds_read_b128 v[10:13], v3 offset:13376
	ds_read_b128 v[2:5], v3 offset:13408
	s_waitcnt lgkmcnt(9)
	v_mfma_f32_32x32x16_bf16 v[48:63], v[194:197], v[92:95], v[48:63]
	s_waitcnt lgkmcnt(8)
	v_mfma_f32_32x32x16_bf16 v[48:63], v[198:201], v[96:99], v[48:63]
	v_max3_f32 v14, v64, s36, v65
	v_max3_f32 v14, v14, v66, v67
	v_max3_f32 v14, v14, v68, v69
	v_max3_f32 v14, v14, v70, v71
	v_max3_f32 v14, v14, v72, v73
	v_max3_f32 v14, v14, v74, v75
	v_max3_f32 v14, v14, v76, v77
	v_max3_f32 v14, v14, v78, v79
	s_nop 3
	v_max3_f32 v14, v14, v48, v49
	v_max3_f32 v14, v14, v50, v51
	v_max3_f32 v14, v14, v52, v53
	v_max3_f32 v14, v14, v54, v55
	v_max3_f32 v14, v14, v56, v57
	v_max3_f32 v14, v14, v58, v59
	v_max3_f32 v14, v14, v60, v61
	v_max3_f32 v14, v14, v62, v63
	v_mul_f32_e32 v14, 0x3e16c740, v14
	v_cmp_lt_i32_e32 vcc, v183, v184
	v_max_f32_e32 v0, v0, v14
	s_nop 0
	v_cndmask_b32_e32 v14, v182, v183, vcc
	v_lshlrev_b32_e32 v14, 2, v14
	ds_bpermute_b32 v15, v14, v0
	s_waitcnt lgkmcnt(0)
	s_mov_b64 s[100:101], exec
	s_mov_b64 exec, 1
	ds_write_b32 v252, v254
	s_mov_b64 exec, s[100:101]
	v_max_f32_e32 v15, v15, v15
	v_max_f32_e32 v15, v0, v15
	v_fma_f32 v0, v64, s37, -v15
	v_fma_f32 v64, v65, s37, -v15
	v_exp_f32_e32 v65, v0
	v_exp_f32_e32 v64, v64
	v_fma_f32 v0, v66, s37, -v15
	v_exp_f32_e32 v66, v0
	v_fma_f32 v67, v67, s37, -v15
	v_exp_f32_e32 v67, v67
	v_fma_f32 v68, v68, s37, -v15
	v_sub_f32_e32 v0, v186, v15
	v_add_f32_e32 v186, 0, v65
	v_exp_f32_e32 v68, v68
	v_fma_f32 v69, v69, s37, -v15
	v_add_f32_e32 v186, v64, v186
	v_exp_f32_e32 v69, v69
	v_fma_f32 v70, v70, s37, -v15
	v_add_f32_e32 v186, v66, v186
	v_exp_f32_e32 v70, v70
	v_fma_f32 v71, v71, s37, -v15
	v_add_f32_e32 v186, v67, v186
	v_exp_f32_e32 v71, v71
	v_fma_f32 v72, v72, s37, -v15
	v_add_f32_e32 v186, v68, v186
	v_exp_f32_e32 v72, v72
	v_fma_f32 v73, v73, s37, -v15
	v_add_f32_e32 v186, v69, v186
	v_exp_f32_e32 v73, v73
	v_fma_f32 v74, v74, s37, -v15
	v_add_f32_e32 v186, v70, v186
	v_exp_f32_e32 v74, v74
	v_fma_f32 v75, v75, s37, -v15
	v_add_f32_e32 v186, v71, v186
	v_exp_f32_e32 v75, v75
	v_fma_f32 v76, v76, s37, -v15
	v_add_f32_e32 v186, v72, v186
	v_exp_f32_e32 v76, v76
	v_fma_f32 v77, v77, s37, -v15
	v_add_f32_e32 v186, v73, v186
	v_exp_f32_e32 v77, v77
	v_fma_f32 v78, v78, s37, -v15
	v_add_f32_e32 v186, v74, v186
	v_exp_f32_e32 v78, v78
	v_fma_f32 v79, v79, s37, -v15
	v_add_f32_e32 v186, v75, v186
	v_exp_f32_e32 v79, v79
	v_fma_f32 v48, v48, s37, -v15
	v_add_f32_e32 v186, v76, v186
	v_exp_f32_e32 v187, v48
	v_fma_f32 v48, v49, s37, -v15
	v_add_f32_e32 v186, v77, v186
	v_exp_f32_e32 v188, v48
	v_fma_f32 v48, v50, s37, -v15
	v_add_f32_e32 v186, v78, v186
	v_exp_f32_e32 v189, v48
	v_fma_f32 v49, v51, s37, -v15
	v_add_f32_e32 v48, v79, v186
	v_exp_f32_e32 v186, v49
	v_fma_f32 v49, v52, s37, -v15
	v_add_f32_e32 v48, v187, v48
	v_exp_f32_e32 v52, v49
	v_fma_f32 v49, v53, s37, -v15
	v_add_f32_e32 v48, v188, v48
	v_exp_f32_e32 v53, v49
	v_fma_f32 v49, v54, s37, -v15
	v_add_f32_e32 v48, v189, v48
	v_exp_f32_e32 v54, v49
	v_add_f32_e32 v48, v186, v48
	v_add_f32_e32 v48, v52, v48
	v_exp_f32_e32 v0, v0
	v_add_f32_e32 v48, v53, v48
	v_add_f32_e32 v190, v54, v48
	v_fma_f32 v48, v55, s37, -v15
	v_exp_f32_e32 v55, v48
	v_fma_f32 v48, v56, s37, -v15
	v_exp_f32_e32 v56, v48
	v_pk_mul_f32 v[46:47], v[46:47], v[0:1] op_sel_hi:[1,0]
	v_pk_mul_f32 v[44:45], v[44:45], v[0:1] op_sel_hi:[1,0]
	v_pk_mul_f32 v[42:43], v[42:43], v[0:1] op_sel_hi:[1,0]
	v_pk_mul_f32 v[40:41], v[40:41], v[0:1] op_sel_hi:[1,0]
	v_pk_mul_f32 v[38:39], v[38:39], v[0:1] op_sel_hi:[1,0]
	v_pk_mul_f32 v[36:37], v[36:37], v[0:1] op_sel_hi:[1,0]
	v_pk_mul_f32 v[34:35], v[34:35], v[0:1] op_sel_hi:[1,0]
; template <int DQK, bool MASKED, int MODE, class MF>
; DI void attn_step(const bf16_t* sK, const bf16_t* sVt, const bf16x8 (&qf)[DQK / 16], f32x16& o0, f32x16& o1, float& m, float& l,
;                   float sc, const MF& mf, int lane, f32x16 (&s)[2], float invl, bool lanevalid = true) {
;     ...
;     for (int ks = 0; ks < DQK / 16; ++ks) kf[sub][ks] = *(const bf16x8*)(sK + (sub * 32 + pr) * KST + ks * 16 + 8 * h);
;   __builtin_amdgcn_sched_barrier(0);
; #pragma unroll
;   for (int q = 0; q < 16; ++q) { s[0][q] = 0.f; s[1][q] = 0.f; }
; #pragma unroll
;   for (int ks = 0; ks < DQK / 16; ++ks) {
;     s[0] = MFMA(kf[0][ks], qf[ks], s[0]);
;     s[1] = MFMA(kf[1][ks], qf[ks], s[1]);
;   }
;   bf16x8 vf[2][2][2];
;   if (MODE != 1) {
; #pragma unroll
;     for (int sub = 0; sub < 2; ++sub)
; #pragma unroll
;       for (int s2 = 0; s2 < 2; ++s2) {
;         vf[sub][s2][0] = *(const bf16x8*)(sVt + r * 72 + sub * 32 + s2 * 16 + 8 * h);
;         vf[sub][s2][1] = *(const bf16x8*)(sVt + (32 + r) * 72 + sub * 32 + s2 * 16 + 8 * h);
;       }
;     __builtin_amdgcn_sched_barrier(0);
;   }
;   float mxr = -3.0e38f;
; #pragma unroll
;   for (int sub = 0; sub < 2; ++sub)
; #pragma unroll
;     for (int q = 0; q < 16; ++q) {
;       if (MASKED) { const int kk = sub * 32 + 16 * (q >> 3) + 8 * h + (q & 7); s[sub][q] = mf(kk) ? s[sub][q] : -3.0e38f; }
;       if (MODE != 2) mxr = fmaxf(mxr, s[sub][q]);
;     }
;   float alpha = 1.f;
;   if (MODE != 2) {
;     float mx = fmaxf(m, mxr * sc);
;     mx = fmaxf(mx, shx(mx, 32));
;     if (!MASKED) mx = lanevalid ? mx : m;
;     alpha = fexp2(m - mx);
;     m = mx;
;   }
;   const float moff = (!MASKED && !lanevalid) ? 1.0e30f : m;
;   float ps = 0.f;
; #pragma unroll
;   for (int sub = 0; sub < 2; ++sub)
; #pragma unroll
;     for (int q = 0; q < 16; ++q) {
;       float pv = fexp2(__builtin_fmaf(s[sub][q], sc, -moff));
;       if (MASKED && MODE != 0) pv = (s[sub][q] > -1.0e38f) ? pv : 0.f;
;       if (MODE == 2) pv *= invl;
;       s[sub][q] = pv;
;       ps += pv;
;     }
;   if (MODE != 2) {
;     ps += shx(ps, 32);
;     l = l * alpha + ps;
;   }
;   if (MODE == 1) return;
;   if (MODE == 0) {
; #pragma unroll
;     for (int q = 0; q < 16; ++q) { o0[q] *= alpha; o1[q] *= alpha; }
;   }
; #pragma unroll
;   for (int sub = 0; sub < 2; ++sub)
; #pragma unroll
;     for (int s2 = 0; s2 < 2; ++s2) {
	v_pk_mul_f32 v[32:33], v[32:33], v[0:1] op_sel_hi:[1,0]
	v_cvt_pk_bf16_f32 v48, v65, v64
	v_cvt_pk_bf16_f32 v49, v66, v67
	v_cvt_pk_bf16_f32 v50, v68, v69
	v_cvt_pk_bf16_f32 v51, v70, v71
	v_pk_mul_f32 v[30:31], v[30:31], v[0:1] op_sel_hi:[1,0]
	v_pk_mul_f32 v[28:29], v[28:29], v[0:1] op_sel_hi:[1,0]
	v_mfma_f32_32x32x16_bf16 v[32:47], v[132:135], v[48:51], v[32:47]
	v_mul_f32_e64 v26, v26, v0
	v_mul_f32_e64 v27, v27, v0
	v_mul_f32_e64 v24, v24, v0
	v_mul_f32_e64 v25, v25, v0
	v_mul_f32_e64 v22, v22, v0
	v_mul_f32_e64 v23, v23, v0
	v_pk_mul_f32 v[20:21], v[20:21], v[0:1] op_sel_hi:[1,0]
	v_pk_mul_f32 v[18:19], v[18:19], v[0:1] op_sel_hi:[1,0]
	v_pk_mul_f32 v[16:17], v[16:17], v[0:1] op_sel_hi:[1,0]
	v_fma_f32 v57, v57, s37, -v15
	v_exp_f32_e32 v57, v57
	v_mfma_f32_32x32x16_bf16 v[16:31], v[128:131], v[48:51], v[16:31]
	v_add_f32_e32 v48, v55, v190
	v_add_f32_e32 v64, v56, v48
	v_cvt_pk_bf16_f32 v48, v72, v73
	v_cvt_pk_bf16_f32 v49, v74, v75
	v_cvt_pk_bf16_f32 v50, v76, v77
	v_cvt_pk_bf16_f32 v51, v78, v79
	v_fma_f32 v58, v58, s37, -v15
	v_exp_f32_e32 v58, v58
	v_mfma_f32_32x32x16_bf16 v[32:47], v[124:127], v[48:51], v[32:47]
	v_fma_f32 v59, v59, s37, -v15
	v_exp_f32_e32 v59, v59
	v_add_f32_e32 v64, v57, v64
	v_add_f32_e32 v64, v58, v64
	v_add_f32_e32 v64, v59, v64
	v_mfma_f32_32x32x16_bf16 v[16:31], v[120:123], v[48:51], v[16:31]
	v_fma_f32 v48, v60, s37, -v15
	v_exp_f32_e32 v60, v48
	v_cvt_pk_bf16_f32 v48, v187, v188
	v_cvt_pk_bf16_f32 v49, v189, v186
	v_cvt_pk_bf16_f32 v50, v52, v53
	v_cvt_pk_bf16_f32 v51, v54, v55
	v_fma_f32 v53, v61, s37, -v15
	v_exp_f32_e32 v53, v53
	v_mfma_f32_32x32x16_bf16 v[32:47], v[116:119], v[48:51], v[32:47]
	v_fma_f32 v54, v62, s37, -v15
	v_exp_f32_e32 v54, v54
	v_fma_f32 v55, v63, s37, -v15
	v_exp_f32_e32 v55, v55
	v_add_f32_e32 v52, v60, v64
	v_mov_b32_e32 v186, v15
	v_mfma_f32_32x32x16_bf16 v[16:31], v[10:13], v[48:51], v[16:31]
	v_add_f32_e32 v10, v53, v52
	v_add_f32_e32 v10, v54, v10
	v_add_f32_e32 v48, v55, v10
	v_cvt_pk_bf16_f32 v10, v56, v57
	v_cvt_pk_bf16_f32 v11, v58, v59
	v_cvt_pk_bf16_f32 v12, v60, v53
	v_cvt_pk_bf16_f32 v13, v54, v55
	s_nop 1
	v_mfma_f32_32x32x16_bf16 v[32:47], v[6:9], v[10:13], v[32:47]
	s_nop 1
	v_mfma_f32_32x32x16_bf16 v[16:31], v[2:5], v[10:13], v[16:31]
	v_fma_f32 v6, v165, v0, v48
	v_mov_b32_e32 v165, v6
.LBB0_788:
	s_andn2_saveexec_b64 s[24:25], s[24:25]
	s_cbranch_execz .LBB0_790
	v_lshl_add_u32 v14, s40, 1, v176
	ds_read_b128 v[2:5], v14
	ds_read_b128 v[6:9], v14 offset:32
	ds_read_b128 v[10:13], v14 offset:64
	ds_read_b128 v[116:119], v14 offset:96
	ds_read_b128 v[120:123], v14 offset:128
	ds_read_b128 v[124:127], v14 offset:160
	ds_read_b128 v[48:51], v14 offset:6656
	ds_read_b128 v[128:131], v14 offset:6688
	ds_read_b128 v[132:135], v14 offset:6720
	ds_read_b128 v[188:191], v14 offset:6752
	ds_read_b128 v[194:197], v14 offset:6784
	ds_read_b128 v[198:201], v14 offset:6816
	s_waitcnt lgkmcnt(11)
	v_mfma_f32_32x32x16_bf16 v[64:79], v[2:5], v[100:103], 0
	v_lshlrev_b32_e32 v2, 1, v175
	v_add3_u32 v3, s39, v172, v2
	v_add3_u32 v2, s39, v173, v2
	s_waitcnt lgkmcnt(10)
	v_mfma_f32_32x32x16_bf16 v[64:79], v[6:9], v[80:83], v[64:79]
	s_waitcnt lgkmcnt(5)
	v_mfma_f32_32x32x16_bf16 v[48:63], v[48:51], v[100:103], 0
	v_mfma_f32_32x32x16_bf16 v[64:79], v[10:13], v[84:87], v[64:79]
	s_waitcnt lgkmcnt(4)
	v_mfma_f32_32x32x16_bf16 v[48:63], v[128:131], v[80:83], v[48:63]
	v_mfma_f32_32x32x16_bf16 v[64:79], v[116:119], v[88:91], v[64:79]
	s_waitcnt lgkmcnt(3)
	v_mfma_f32_32x32x16_bf16 v[48:63], v[132:135], v[84:87], v[48:63]
	v_mfma_f32_32x32x16_bf16 v[64:79], v[120:123], v[92:95], v[64:79]
	s_waitcnt lgkmcnt(2)
	v_mfma_f32_32x32x16_bf16 v[48:63], v[188:191], v[88:91], v[48:63]
	v_mfma_f32_32x32x16_bf16 v[64:79], v[124:127], v[96:99], v[64:79]
	ds_read_b128 v[132:135], v3 offset:13312
	ds_read_b128 v[124:127], v3 offset:13344
	ds_read_b128 v[128:131], v2 offset:13312
	ds_read_b128 v[120:123], v2 offset:13344
	ds_read_b128 v[116:119], v3 offset:13376
	ds_read_b128 v[6:9], v3 offset:13408
	ds_read_b128 v[10:13], v2 offset:13376
	ds_read_b128 v[2:5], v2 offset:13408
	s_waitcnt lgkmcnt(9)
	v_mfma_f32_32x32x16_bf16 v[48:63], v[194:197], v[92:95], v[48:63]
	s_waitcnt lgkmcnt(8)
	v_mfma_f32_32x32x16_bf16 v[48:63], v[198:201], v[96:99], v[48:63]
	v_add_u32_e32 v14, s14, v175
	v_cmp_le_i32_e32 vcc, v14, v164
	s_nop 1
	v_cndmask_b32_e32 v15, v185, v64, vcc
	v_cmp_lt_i32_e32 vcc, v14, v164
	s_nop 1
	v_cndmask_b32_e32 v64, v185, v65, vcc
	v_add_u32_e32 v65, 2, v14
	v_cmp_le_i32_e32 vcc, v65, v164
	s_nop 1
	v_cndmask_b32_e32 v65, v185, v66, vcc
	v_add_u32_e32 v66, 3, v14
	v_cmp_le_i32_e32 vcc, v66, v164
	s_nop 1
	v_cndmask_b32_e32 v66, v185, v67, vcc
	v_add_u32_e32 v67, 4, v14
	v_cmp_le_i32_e32 vcc, v67, v164
	s_nop 1
	v_cndmask_b32_e32 v67, v185, v68, vcc
	v_add_u32_e32 v68, 5, v14
	v_cmp_le_i32_e32 vcc, v68, v164
	s_nop 1
	v_cndmask_b32_e32 v68, v185, v69, vcc
	v_add_u32_e32 v69, 6, v14
	v_cmp_le_i32_e32 vcc, v69, v164
	s_nop 1
	v_cndmask_b32_e32 v69, v185, v70, vcc
	v_add_u32_e32 v70, s14, v174
	v_or_b32_e32 v187, 7, v70
	v_cmp_le_i32_e32 vcc, v187, v164
	v_add_u32_e32 v187, 16, v14
	s_nop 0
	v_cndmask_b32_e32 v71, v185, v71, vcc
	v_cmp_le_i32_e32 vcc, v187, v164
	v_add_u32_e32 v187, 17, v14
	s_nop 0
	v_cndmask_b32_e32 v72, v185, v72, vcc
	v_cmp_le_i32_e32 vcc, v187, v164
	v_add_u32_e32 v187, 18, v14
	s_nop 0
	v_cndmask_b32_e32 v73, v185, v73, vcc
	v_cmp_le_i32_e32 vcc, v187, v164
	v_add_u32_e32 v187, 19, v14
	s_nop 0
	v_cndmask_b32_e32 v74, v185, v74, vcc
	v_cmp_le_i32_e32 vcc, v187, v164
	v_add_u32_e32 v187, 20, v14
	s_nop 0
	v_cndmask_b32_e32 v75, v185, v75, vcc
	v_cmp_le_i32_e32 vcc, v187, v164
; DI float shx(float v, int m) { return __shfl_xor(v, m, 64); }
; template <int DQK, bool MASKED, int MODE, class MF>
; DI void attn_step(const bf16_t* sK, const bf16_t* sVt, const bf16x8 (&qf)[DQK / 16], f32x16& o0, f32x16& o1, float& m, float& l,
;                   float sc, const MF& mf, int lane, f32x16 (&s)[2], float invl, bool lanevalid = true) {
;     ...
;       if (MASKED) { const int kk = sub * 32 + 16 * (q >> 3) + 8 * h + (q & 7); s[sub][q] = mf(kk) ? s[sub][q] : -3.0e38f; }
;       if (MODE != 2) mxr = fmaxf(mxr, s[sub][q]);
;     }
;   float alpha = 1.f;
;   if (MODE != 2) {
;     float mx = fmaxf(m, mxr * sc);
;     mx = fmaxf(mx, shx(mx, 32));
	v_add_u32_e32 v187, 21, v14
	s_nop 0
	v_cndmask_b32_e32 v76, v185, v76, vcc
	v_cmp_le_i32_e32 vcc, v187, v164
	v_add_u32_e32 v187, 22, v14
	s_nop 0
	v_cndmask_b32_e32 v77, v185, v77, vcc
	v_cmp_le_i32_e32 vcc, v187, v164
	v_or_b32_e32 v187, 23, v70
	s_nop 0
	v_cndmask_b32_e32 v78, v185, v78, vcc
	v_cmp_le_i32_e32 vcc, v187, v164
	v_add_u32_e32 v187, 32, v14
	s_nop 0
	v_cndmask_b32_e32 v79, v185, v79, vcc
	v_cmp_le_i32_e32 vcc, v187, v164
	v_add_u32_e32 v187, 33, v14
	s_nop 0
	v_cndmask_b32_e32 v48, v185, v48, vcc
	v_cmp_le_i32_e32 vcc, v187, v164
	v_add_u32_e32 v187, 34, v14
	s_nop 0
	v_cndmask_b32_e32 v49, v185, v49, vcc
	v_cmp_le_i32_e32 vcc, v187, v164
	v_add_u32_e32 v187, 35, v14
	s_nop 0
	v_cndmask_b32_e32 v50, v185, v50, vcc
	v_cmp_le_i32_e32 vcc, v187, v164
	v_add_u32_e32 v187, 36, v14
	s_nop 0
	v_cndmask_b32_e32 v51, v185, v51, vcc
	v_cmp_le_i32_e32 vcc, v187, v164
	v_add_u32_e32 v187, 37, v14
	s_nop 0
	v_cndmask_b32_e32 v52, v185, v52, vcc
	v_cmp_le_i32_e32 vcc, v187, v164
	v_add_u32_e32 v187, 38, v14
	s_nop 0
	v_cndmask_b32_e32 v53, v185, v53, vcc
	v_cmp_le_i32_e32 vcc, v187, v164
	v_or_b32_e32 v187, 39, v70
	s_nop 0
	v_cndmask_b32_e32 v54, v185, v54, vcc
	v_cmp_le_i32_e32 vcc, v187, v164
	v_add_u32_e32 v187, 48, v14
	s_nop 0
	v_cndmask_b32_e32 v55, v185, v55, vcc
	v_cmp_le_i32_e32 vcc, v187, v164
	v_add_u32_e32 v187, 49, v14
	s_nop 0
	v_cndmask_b32_e32 v56, v185, v56, vcc
	v_cmp_le_i32_e32 vcc, v187, v164
	v_add_u32_e32 v187, 50, v14
	s_nop 0
	v_cndmask_b32_e32 v57, v185, v57, vcc
	v_cmp_le_i32_e32 vcc, v187, v164
	v_add_u32_e32 v187, 51, v14
	s_nop 0
	v_cndmask_b32_e32 v58, v185, v58, vcc
	v_cmp_le_i32_e32 vcc, v187, v164
	v_add_u32_e32 v187, 52, v14
	s_nop 0
	v_cndmask_b32_e32 v59, v185, v59, vcc
	v_cmp_le_i32_e32 vcc, v187, v164
	v_add_u32_e32 v187, 53, v14
	v_add_u32_e32 v14, 54, v14
	v_cndmask_b32_e32 v60, v185, v60, vcc
	v_cmp_le_i32_e32 vcc, v187, v164
	s_nop 1
	v_cndmask_b32_e32 v61, v185, v61, vcc
	v_cmp_le_i32_e32 vcc, v14, v164
	s_nop 1
	v_cndmask_b32_e32 v14, v185, v62, vcc
	v_or_b32_e32 v62, 55, v70
	v_cmp_le_i32_e32 vcc, v62, v164
	s_nop 1
	v_cndmask_b32_e32 v62, v185, v63, vcc
	v_max3_f32 v63, v15, s36, v64
	v_max3_f32 v63, v63, v65, v66
	v_max3_f32 v63, v63, v67, v68
	v_max3_f32 v63, v63, v69, v71
	v_max3_f32 v63, v63, v72, v73
	v_max3_f32 v63, v63, v74, v75
	v_max3_f32 v63, v63, v76, v77
	v_max3_f32 v63, v63, v78, v79
	v_max3_f32 v63, v63, v48, v49
	v_max3_f32 v63, v63, v50, v51
	v_max3_f32 v63, v63, v52, v53
	v_max3_f32 v63, v63, v54, v55
	v_max3_f32 v63, v63, v56, v57
	v_max3_f32 v63, v63, v58, v59
	v_max3_f32 v63, v63, v60, v61
	v_max3_f32 v63, v63, v14, v62
	v_mul_f32_e32 v63, 0x3e16c740, v63
	v_cmp_lt_i32_e32 vcc, v183, v184
	v_max_f32_e32 v0, v0, v63
	s_nop 0
	v_cndmask_b32_e32 v63, v182, v183, vcc
	v_lshlrev_b32_e32 v63, 2, v63
	ds_bpermute_b32 v70, v63, v0
	s_waitcnt lgkmcnt(0)
; #define MFMA(a, b, c) __builtin_amdgcn_mfma_f32_32x32x16_bf16((a), (b), (c), 0, 0, 0)
; DI unsigned pack2(float a, float b) { f32x2_t v = {a, b}; bf16x2_t r = __builtin_convertvector(v, bf16x2_t); return __builtin_bit_cast(unsigned, r); }
; DI float fexp2(float x) { return __builtin_amdgcn_exp2f(x); }
; DI float shx(float v, int m) { return __shfl_xor(v, m, 64); }
; template <int DQK, bool MASKED, int MODE, class MF>
; DI void attn_step(const bf16_t* sK, const bf16_t* sVt, const bf16x8 (&qf)[DQK / 16], f32x16& o0, f32x16& o1, float& m, float& l,
;                   float sc, const MF& mf, int lane, f32x16 (&s)[2], float invl, bool lanevalid = true) {
;     ...
;   float alpha = 1.f;
;   if (MODE != 2) {
;     float mx = fmaxf(m, mxr * sc);
;     mx = fmaxf(mx, shx(mx, 32));
;     if (!MASKED) mx = lanevalid ? mx : m;
;     alpha = fexp2(m - mx);
;     m = mx;
;   }
;   const float moff = (!MASKED && !lanevalid) ? 1.0e30f : m;
;   float ps = 0.f;
; #pragma unroll
;   for (int sub = 0; sub < 2; ++sub)
; #pragma unroll
;     for (int q = 0; q < 16; ++q) {
;       float pv = fexp2(__builtin_fmaf(s[sub][q], sc, -moff));
;       if (MASKED && MODE != 0) pv = (s[sub][q] > -1.0e38f) ? pv : 0.f;
;       if (MODE == 2) pv *= invl;
;       s[sub][q] = pv;
;       ps += pv;
;     }
;   if (MODE != 2) {
;     ps += shx(ps, 32);
;     l = l * alpha + ps;
;   }
;   if (MODE == 1) return;
;   if (MODE == 0) {
; #pragma unroll
;     for (int q = 0; q < 16; ++q) { o0[q] *= alpha; o1[q] *= alpha; }
;   }
; #pragma unroll
;   for (int sub = 0; sub < 2; ++sub)
; #pragma unroll
;     for (int s2 = 0; s2 < 2; ++s2) {
;       union { bf16x8 v; unsigned u[4]; } pb;
; #pragma unroll
;       for (int e = 0; e < 4; ++e) pb.u[e] = pack2(s[sub][8 * s2 + 2 * e], s[sub][8 * s2 + 2 * e + 1]);
;       o0 = MFMA(vf[sub][s2][0], pb.v, o0);
;       o1 = MFMA(vf[sub][s2][1], pb.v, o1);
;     }
	s_mov_b64 s[100:101], exec
	s_mov_b64 exec, 1
	ds_write_b32 v252, v254
	s_mov_b64 exec, s[100:101]
	v_max_f32_e32 v70, v70, v70
	v_max_f32_e32 v70, v0, v70
	v_fma_f32 v0, v15, s37, -v70
	v_exp_f32_e32 v15, v0
	v_fma_f32 v0, v64, s37, -v70
	v_exp_f32_e32 v64, v0
	v_fma_f32 v0, v65, s37, -v70
	v_exp_f32_e32 v65, v0
	v_fma_f32 v66, v66, s37, -v70
	v_exp_f32_e32 v66, v66
	v_fma_f32 v67, v67, s37, -v70
	v_sub_f32_e32 v0, v186, v70
	v_add_f32_e32 v186, 0, v15
	v_exp_f32_e32 v67, v67
	v_fma_f32 v68, v68, s37, -v70
	v_add_f32_e32 v186, v64, v186
	v_exp_f32_e32 v68, v68
	v_fma_f32 v69, v69, s37, -v70
	v_add_f32_e32 v186, v65, v186
	v_exp_f32_e32 v69, v69
	v_fma_f32 v71, v71, s37, -v70
	v_add_f32_e32 v186, v66, v186
	v_exp_f32_e32 v71, v71
	v_fma_f32 v72, v72, s37, -v70
	v_add_f32_e32 v186, v67, v186
	v_exp_f32_e32 v72, v72
	v_fma_f32 v73, v73, s37, -v70
	v_add_f32_e32 v186, v68, v186
	v_exp_f32_e32 v73, v73
	v_fma_f32 v74, v74, s37, -v70
	v_add_f32_e32 v186, v69, v186
	v_exp_f32_e32 v74, v74
	v_fma_f32 v75, v75, s37, -v70
	v_add_f32_e32 v186, v71, v186
	v_exp_f32_e32 v75, v75
	v_fma_f32 v76, v76, s37, -v70
	v_add_f32_e32 v186, v72, v186
	v_exp_f32_e32 v76, v76
	v_fma_f32 v77, v77, s37, -v70
	v_add_f32_e32 v186, v73, v186
	v_exp_f32_e32 v77, v77
	v_fma_f32 v78, v78, s37, -v70
	v_add_f32_e32 v186, v74, v186
	v_exp_f32_e32 v78, v78
	v_fma_f32 v79, v79, s37, -v70
	v_add_f32_e32 v186, v75, v186
	v_exp_f32_e32 v79, v79
	v_fma_f32 v48, v48, s37, -v70
	v_add_f32_e32 v186, v76, v186
	v_exp_f32_e32 v187, v48
	v_fma_f32 v48, v49, s37, -v70
	v_add_f32_e32 v186, v77, v186
	v_exp_f32_e32 v188, v48
	v_fma_f32 v48, v50, s37, -v70
	v_add_f32_e32 v186, v78, v186
	v_exp_f32_e32 v189, v48
	v_fma_f32 v49, v51, s37, -v70
	v_add_f32_e32 v48, v79, v186
	v_exp_f32_e32 v186, v49
	v_fma_f32 v49, v52, s37, -v70
	v_add_f32_e32 v48, v187, v48
	v_exp_f32_e32 v52, v49
	v_fma_f32 v49, v53, s37, -v70
	v_add_f32_e32 v48, v188, v48
	v_exp_f32_e32 v53, v49
	v_fma_f32 v49, v54, s37, -v70
	v_add_f32_e32 v48, v189, v48
	v_exp_f32_e32 v54, v49
	v_add_f32_e32 v48, v186, v48
	v_add_f32_e32 v48, v52, v48
	v_exp_f32_e32 v0, v0
	v_add_f32_e32 v48, v53, v48
	v_add_f32_e32 v190, v54, v48
	v_fma_f32 v48, v55, s37, -v70
	v_exp_f32_e32 v55, v48
	v_fma_f32 v48, v56, s37, -v70
	v_exp_f32_e32 v56, v48
	v_pk_mul_f32 v[46:47], v[46:47], v[0:1] op_sel_hi:[1,0]
	v_pk_mul_f32 v[44:45], v[44:45], v[0:1] op_sel_hi:[1,0]
	v_pk_mul_f32 v[42:43], v[42:43], v[0:1] op_sel_hi:[1,0]
	v_pk_mul_f32 v[40:41], v[40:41], v[0:1] op_sel_hi:[1,0]
	v_pk_mul_f32 v[38:39], v[38:39], v[0:1] op_sel_hi:[1,0]
	v_pk_mul_f32 v[36:37], v[36:37], v[0:1] op_sel_hi:[1,0]
	v_pk_mul_f32 v[34:35], v[34:35], v[0:1] op_sel_hi:[1,0]
	v_pk_mul_f32 v[32:33], v[32:33], v[0:1] op_sel_hi:[1,0]
	v_pk_mul_f32 v[30:31], v[30:31], v[0:1] op_sel_hi:[1,0]
	v_cvt_pk_bf16_f32 v48, v15, v64
	v_cvt_pk_bf16_f32 v49, v65, v66
	v_cvt_pk_bf16_f32 v50, v67, v68
	v_cvt_pk_bf16_f32 v51, v69, v71
	v_pk_mul_f32 v[28:29], v[28:29], v[0:1] op_sel_hi:[1,0]
	v_pk_mul_f32 v[26:27], v[26:27], v[0:1] op_sel_hi:[1,0]
	v_pk_mul_f32 v[24:25], v[24:25], v[0:1] op_sel_hi:[1,0]
	v_pk_mul_f32 v[22:23], v[22:23], v[0:1] op_sel_hi:[1,0]
	v_pk_mul_f32 v[20:21], v[20:21], v[0:1] op_sel_hi:[1,0]
	v_pk_mul_f32 v[18:19], v[18:19], v[0:1] op_sel_hi:[1,0]
	v_pk_mul_f32 v[16:17], v[16:17], v[0:1] op_sel_hi:[1,0]
	v_mfma_f32_32x32x16_bf16 v[32:47], v[132:135], v[48:51], v[32:47]
	v_fma_f32 v57, v57, s37, -v70
	v_exp_f32_e32 v57, v57
	v_fma_f32 v58, v58, s37, -v70
	v_exp_f32_e32 v58, v58
	v_fma_f32 v59, v59, s37, -v70
	v_add_f32_e32 v15, v55, v190
	v_exp_f32_e32 v59, v59
	v_mfma_f32_32x32x16_bf16 v[16:31], v[128:131], v[48:51], v[16:31]
	v_cvt_pk_bf16_f32 v48, v72, v73
	v_cvt_pk_bf16_f32 v49, v74, v75
	v_cvt_pk_bf16_f32 v50, v76, v77
	v_cvt_pk_bf16_f32 v51, v78, v79
	v_add_f32_e32 v15, v56, v15
	v_add_f32_e32 v15, v57, v15
	v_fma_f32 v14, v14, s37, -v70
	v_mfma_f32_32x32x16_bf16 v[32:47], v[124:127], v[48:51], v[32:47]
	v_add_f32_e32 v15, v58, v15
	v_exp_f32_e32 v14, v14
	v_add_f32_e32 v15, v59, v15
	v_mfma_f32_32x32x16_bf16 v[16:31], v[120:123], v[48:51], v[16:31]
	v_fma_f32 v48, v60, s37, -v70
	v_exp_f32_e32 v60, v48
	v_cvt_pk_bf16_f32 v48, v187, v188
	v_cvt_pk_bf16_f32 v49, v189, v186
	v_cvt_pk_bf16_f32 v50, v52, v53
	v_cvt_pk_bf16_f32 v51, v54, v55
	v_fma_f32 v52, v61, s37, -v70
	v_exp_f32_e32 v52, v52
	v_mfma_f32_32x32x16_bf16 v[32:47], v[116:119], v[48:51], v[32:47]
	v_fma_f32 v53, v62, s37, -v70
	v_exp_f32_e32 v53, v53
	v_add_f32_e32 v15, v60, v15
	v_mov_b32_e32 v186, v70
	v_mfma_f32_32x32x16_bf16 v[16:31], v[10:13], v[48:51], v[16:31]
	v_add_f32_e32 v10, v52, v15
	v_add_f32_e32 v10, v14, v10
	v_add_f32_e32 v15, v53, v10
	v_cvt_pk_bf16_f32 v10, v56, v57
	v_cvt_pk_bf16_f32 v11, v58, v59
	v_cvt_pk_bf16_f32 v12, v60, v52
	v_cvt_pk_bf16_f32 v13, v14, v53
	s_nop 1
	v_mfma_f32_32x32x16_bf16 v[32:47], v[6:9], v[10:13], v[32:47]
	s_nop 1
	v_mfma_f32_32x32x16_bf16 v[16:31], v[2:5], v[10:13], v[16:31]
	v_fma_f32 v6, v165, v0, v15
	v_mov_b32_e32 v165, v6

; DI unsigned pack2(float a, float b) { f32x2_t v = {a, b}; bf16x2_t r = __builtin_convertvector(v, bf16x2_t); return __builtin_bit_cast(unsigned, r); }
; DI float bflo(unsigned u) { return __uint_as_float(u << 16); }
; DI float bfhi(unsigned u) { return __uint_as_float(u & 0xffff0000u); }
; DI float siluf_(float x) { return x * __builtin_amdgcn_rcpf(1.f + __expf(-x)); }
; DI void attn_write_staged(const f32x16& o0, const f32x16& o1, bf16_t* og, const bf16_t* z, size_t tok0, int head, int lane, bf16_t* wl) {
;   const int q = lane & 31, h = lane >> 5;
; #pragma unroll
;   for (int dt = 0; dt < 2; ++dt)
; #pragma unroll
;     for (int q4 = 0; q4 < 4; ++q4) {
;       const f32x16& o = dt ? o1 : o0;
;       *(uint2*)(wl + q * 72 + dt * 32 + 8 * q4 + 4 * h) = make_uint2(pack2(o[4 * q4], o[4 * q4 + 1]), pack2(o[4 * q4 + 2], o[4 * q4 + 3]));
;     }
; #pragma unroll
;   for (int k = 0; k < 4; ++k) {
;     const int ci = lane + 64 * k, row = ci >> 3, c8 = ci & 7;
;     const u32x4 ov = *(const u32x4*)(wl + row * 72 + c8 * 8);
;     const size_t off = (tok0 + row) * 1024 + head * 64 + c8 * 8;
;     const u32x4 zv = ldg16(z + off);
;     u32x4 r;
;     r.x = pack2(bflo(ov.x) * siluf_(bflo(zv.x)), bfhi(ov.x) * siluf_(bfhi(zv.x)));
;     r.y = pack2(bflo(ov.y) * siluf_(bflo(zv.y)), bfhi(ov.y) * siluf_(bfhi(zv.y)));
;     r.z = pack2(bflo(ov.z) * siluf_(bflo(zv.z)), bfhi(ov.z) * siluf_(bfhi(zv.z)));
;     r.w = pack2(bflo(ov.w) * siluf_(bflo(zv.w)), bfhi(ov.w) * siluf_(bfhi(zv.w)));
;     *(u32x4*)(og + off) = r;
;   }
; DI void tot_addto(float* totL, int tid, f32x16& a, f32x16& b, float gi) {
; #pragma unroll
;   for (int k = 0; k < 4; ++k) {
;     const f32x4 v0 = *(const f32x4*)(totL + ((size_t)(k * 256 + tid)) * 4);
;     const f32x4 v1 = *(const f32x4*)(totL + ((size_t)((4 + k) * 256 + tid)) * 4);
;     a[4 * k] = v0.x + gi * a[4 * k]; a[4 * k + 1] = v0.y + gi * a[4 * k + 1]; a[4 * k + 2] = v0.z + gi * a[4 * k + 2]; a[4 * k + 3] = v0.w + gi * a[4 * k + 3];
;     b[4 * k] = v1.x + gi * b[4 * k]; b[4 * k + 1] = v1.y + gi * b[4 * k + 1]; b[4 * k + 2] = v1.z + gi * b[4 * k + 2]; b[4 * k + 3] = v1.w + gi * b[4 * k + 3];
;   }
.LBB0_1273:
	ds_bpermute_b32 v247, v173, v40
	s_waitcnt lgkmcnt(0)
	v_add_f32_e32 v40, v40, v247
	s_mov_b32 s47, s45
	v_lshlrev_b32_e32 v41, 3, v137
	v_lshl_add_u64 v[34:35], v[134:135], 0, s[46:47]
	v_lshrrev_b32_e32 v0, 3, v137
	v_and_b32_e32 v41, 56, v41
	v_or_b32_e32 v70, v176, v41
	v_or_b32_e32 v34, v0, v34
	v_lshlrev_b64 v[74:75], 11, v[34:35]
	v_lshlrev_b32_e32 v76, 1, v70
	v_readlane_b32 s2, v246, 52
	v_or_b32_e32 v74, v74, v76
	v_readlane_b32 s3, v246, 53
	ds_read_b128 v[36:39], v180 offset:37376
	s_waitcnt vmcnt(3)
	ds_read_b128 v[42:45], v180 offset:41472
	s_waitcnt vmcnt(2)
	ds_read_b128 v[46:49], v180 offset:53760
	s_waitcnt vmcnt(1)
	ds_read_b128 v[50:53], v180 offset:57856
	s_waitcnt vmcnt(0)
	ds_read_b128 v[54:57], v180 offset:45568
	ds_read_b128 v[58:61], v180 offset:49664
	ds_read_b128 v[62:65], v180 offset:61952
	ds_read_b128 v[66:69], v181 offset:28672
	v_lshl_add_u64 v[70:71], s[2:3], 0, v[74:75]
	s_waitcnt lgkmcnt(0)
	s_barrier
	v_mov_b32_e32 v254, 0x4000
	v_mov_b32_e32 v255, 0
	v_lshl_add_u64 v[248:249], v[70:71], 0, v[254:255]
	v_lshl_add_u64 v[250:251], v[248:249], 0, v[254:255]
	v_lshl_add_u64 v[252:253], v[250:251], 0, v[254:255]
	global_load_dwordx4 v[70:73], v[70:71], off
	global_load_dwordx4 v[90:93], v[248:249], off
	global_load_dwordx4 v[94:97], v[250:251], off
	global_load_dwordx4 v[98:101], v[252:253], off
	v_div_scale_f32 v77, s[0:1], v40, v40, v179
	v_rcp_f32_e32 v81, v77
	s_movk_i32 s0, 0x1200
	v_mad_u32_u24 v80, v168, s0, v153
	v_mul_u32_u24_e32 v0, 0x90, v0
	v_lshlrev_b32_e32 v41, 1, v41
	v_add3_u32 v41, v80, v41, v0
	v_fma_f32 v0, -v77, v81, 1.0
	v_div_scale_f32 v78, vcc, v179, v40, v179
	v_lshrrev_b32_e32 v79, 2, v137
	v_fmac_f32_e32 v81, v0, v81
	v_and_b32_e32 v79, 8, v79
	v_mul_f32_e32 v0, v78, v81
	v_add3_u32 v79, v80, v175, v79
	v_fma_f32 v80, -v77, v0, v78
	v_fmac_f32_e32 v0, v80, v81
	v_fma_f32 v77, -v77, v0, v78
	v_div_fmas_f32 v0, v77, v81, v0
	v_div_fixup_f32 v0, v0, v40, v179
	v_pk_fma_f32 v[2:3], v[0:1], v[2:3], v[36:37] op_sel_hi:[0,1,1]
	v_pk_fma_f32 v[4:5], v[0:1], v[4:5], v[38:39] op_sel_hi:[0,1,1]
	v_pk_fma_f32 v[18:19], v[18:19], v[0:1], v[46:47] op_sel_hi:[1,0,1]
	v_pk_fma_f32 v[6:7], v[0:1], v[6:7], v[42:43] op_sel_hi:[0,1,1]
	v_pk_fma_f32 v[8:9], v[0:1], v[8:9], v[44:45] op_sel_hi:[0,1,1]
	v_pk_fma_f32 v[10:11], v[0:1], v[10:11], v[54:55] op_sel_hi:[0,1,1]
	v_pk_fma_f32 v[20:21], v[20:21], v[0:1], v[48:49] op_sel_hi:[1,0,1]
	v_pk_fma_f32 v[22:23], v[22:23], v[0:1], v[50:51] op_sel_hi:[1,0,1]
	v_pk_fma_f32 v[24:25], v[24:25], v[0:1], v[52:53] op_sel_hi:[1,0,1]
	v_pk_fma_f32 v[12:13], v[0:1], v[12:13], v[56:57] op_sel_hi:[0,1,1]
	v_pk_fma_f32 v[26:27], v[26:27], v[0:1], v[62:63] op_sel_hi:[1,0,1]
	v_pk_fma_f32 v[28:29], v[28:29], v[0:1], v[64:65] op_sel_hi:[1,0,1]
	v_pk_fma_f32 v[14:15], v[0:1], v[14:15], v[58:59] op_sel_hi:[0,1,1]
	v_pk_fma_f32 v[16:17], v[0:1], v[16:17], v[60:61] op_sel_hi:[0,1,1]
	v_pk_fma_f32 v[30:31], v[30:31], v[0:1], v[66:67] op_sel_hi:[1,0,1]
	v_pk_fma_f32 v[32:33], v[32:33], v[0:1], v[68:69] op_sel_hi:[1,0,1]
	v_cvt_pk_bf16_f32 v2, v2, v3
	v_cvt_pk_bf16_f32 v3, v4, v5
	v_cvt_pk_bf16_f32 v4, v6, v7
	v_cvt_pk_bf16_f32 v5, v8, v9
	v_cvt_pk_bf16_f32 v6, v10, v11
	v_cvt_pk_bf16_f32 v10, v18, v19
	v_cvt_pk_bf16_f32 v7, v12, v13
	v_cvt_pk_bf16_f32 v8, v14, v15
	v_cvt_pk_bf16_f32 v9, v16, v17
	v_cvt_pk_bf16_f32 v11, v20, v21
	v_cvt_pk_bf16_f32 v12, v22, v23
	v_cvt_pk_bf16_f32 v13, v24, v25
	v_cvt_pk_bf16_f32 v14, v26, v27
	v_cvt_pk_bf16_f32 v15, v28, v29
	v_cvt_pk_bf16_f32 v16, v30, v31
	v_cvt_pk_bf16_f32 v17, v32, v33
	ds_write2_b64 v79, v[2:3], v[4:5] offset1:2
	ds_write2_b64 v79, v[6:7], v[8:9] offset0:4 offset1:6
	ds_write2_b64 v79, v[10:11], v[12:13] offset0:8 offset1:10
	ds_write2_b64 v79, v[14:15], v[16:17] offset0:12 offset1:14
	ds_read_b128 v[2:5], v41
	ds_read_b128 v[6:9], v41 offset:1152
	s_waitcnt lgkmcnt(1)
	v_and_b32_e32 v13, 0xffff0000, v2
	s_waitcnt vmcnt(3)
	v_lshlrev_b32_e32 v10, 16, v70
	v_and_b32_e32 v11, 0xffff0000, v70
	v_mul_f32_e32 v0, 0xbfb8aa3b, v10
	v_mul_f32_e32 v12, 0xbfb8aa3b, v11
	v_exp_f32_e32 v0, v0
	v_exp_f32_e32 v14, v12
	v_lshlrev_b32_e32 v16, 16, v71
	v_lshlrev_b32_e32 v12, 16, v2
	v_add_f32_e32 v0, 1.0, v0
	v_add_f32_e32 v2, 1.0, v14
	v_rcp_f32_e32 v14, v0
	v_and_b32_e32 v17, 0xffff0000, v71
	v_mul_f32_e32 v0, 0xbfb8aa3b, v16
	v_rcp_f32_e32 v15, v2
	v_exp_f32_e32 v0, v0
	v_mul_f32_e32 v2, 0xbfb8aa3b, v17
	v_exp_f32_e32 v2, v2
	v_pk_mul_f32 v[10:11], v[14:15], v[10:11]
	v_add_f32_e32 v0, 1.0, v0
	v_pk_mul_f32 v[10:11], v[10:11], v[12:13]
	v_rcp_f32_e32 v12, v0
	v_add_f32_e32 v0, 1.0, v2
	v_lshlrev_b32_e32 v14, 16, v72
	v_rcp_f32_e32 v13, v0
	v_and_b32_e32 v15, 0xffff0000, v72
	v_mul_f32_e32 v0, 0xbfb8aa3b, v14
	v_cvt_pk_bf16_f32 v2, v10, v11
	v_lshlrev_b32_e32 v10, 16, v3
	v_and_b32_e32 v11, 0xffff0000, v3
	v_exp_f32_e32 v0, v0
	v_mul_f32_e32 v3, 0xbfb8aa3b, v15
	v_exp_f32_e32 v3, v3
	v_pk_mul_f32 v[12:13], v[12:13], v[16:17]
	v_add_f32_e32 v0, 1.0, v0
	v_pk_mul_f32 v[10:11], v[12:13], v[10:11]
	v_rcp_f32_e32 v12, v0
	v_add_f32_e32 v0, 1.0, v3
	v_rcp_f32_e32 v13, v0
	v_cvt_pk_bf16_f32 v3, v10, v11
	v_lshlrev_b32_e32 v10, 16, v4
	v_and_b32_e32 v11, 0xffff0000, v4
	v_pk_mul_f32 v[12:13], v[12:13], v[14:15]
	v_lshlrev_b32_e32 v14, 16, v73
	v_and_b32_e32 v15, 0xffff0000, v73
	v_mul_f32_e32 v0, 0xbfb8aa3b, v14
	v_exp_f32_e32 v0, v0
	v_mul_f32_e32 v4, 0xbfb8aa3b, v15
	v_exp_f32_e32 v4, v4
	v_pk_mul_f32 v[10:11], v[12:13], v[10:11]
	v_add_f32_e32 v0, 1.0, v0
	v_rcp_f32_e32 v12, v0
	v_add_f32_e32 v0, 1.0, v4
	v_rcp_f32_e32 v13, v0
	v_cvt_pk_bf16_f32 v4, v10, v11
	v_lshlrev_b32_e32 v10, 16, v5
	v_and_b32_e32 v11, 0xffff0000, v5
	v_pk_mul_f32 v[12:13], v[12:13], v[14:15]
	s_waitcnt lgkmcnt(0)
; DI unsigned pack2(float a, float b) { f32x2_t v = {a, b}; bf16x2_t r = __builtin_convertvector(v, bf16x2_t); return __builtin_bit_cast(unsigned, r); }
; DI float bflo(unsigned u) { return __uint_as_float(u << 16); }
; DI float bfhi(unsigned u) { return __uint_as_float(u & 0xffff0000u); }
; DI float siluf_(float x) { return x * __builtin_amdgcn_rcpf(1.f + __expf(-x)); }
; DI void attn_write_staged(const f32x16& o0, const f32x16& o1, bf16_t* og, const bf16_t* z, size_t tok0, int head, int lane, bf16_t* wl) {
;     ...
; #pragma unroll
;   for (int k = 0; k < 4; ++k) {
;     const int ci = lane + 64 * k, row = ci >> 3, c8 = ci & 7;
;     const u32x4 ov = *(const u32x4*)(wl + row * 72 + c8 * 8);
;     const size_t off = (tok0 + row) * 1024 + head * 64 + c8 * 8;
;     const u32x4 zv = ldg16(z + off);
;     u32x4 r;
;     r.x = pack2(bflo(ov.x) * siluf_(bflo(zv.x)), bfhi(ov.x) * siluf_(bfhi(zv.x)));
;     r.y = pack2(bflo(ov.y) * siluf_(bflo(zv.y)), bfhi(ov.y) * siluf_(bfhi(zv.y)));
;     r.z = pack2(bflo(ov.z) * siluf_(bflo(zv.z)), bfhi(ov.z) * siluf_(bfhi(zv.z)));
;     r.w = pack2(bflo(ov.w) * siluf_(bflo(zv.w)), bfhi(ov.w) * siluf_(bfhi(zv.w)));
;     *(u32x4*)(og + off) = r;
;   }
; DI void phase_attn_nsa(const Params& P, bf16_t* og, unsigned char* smem, int L, int G) {
;     ...
;     __syncthreads();
;     attn_write_staged(o0, o1, og, big + NS_Z, (size_t)b * SEQ + t0, head, lane, sK + w * (32 * 72));
;     __syncthreads();
	v_lshlrev_b32_e32 v14, 16, v8
	v_pk_mul_f32 v[10:11], v[12:13], v[10:11]
	v_and_b32_e32 v15, 0xffff0000, v8
	v_cvt_pk_bf16_f32 v5, v10, v11
	v_lshl_add_u64 v[10:11], s[94:95], 0, v[74:75]
	global_store_dwordx4 v[10:11], v[2:5], off
	v_lshlrev_b32_e32 v12, 16, v6
	v_and_b32_e32 v13, 0xffff0000, v6
	v_or_b32_e32 v2, 8, v34
	v_mov_b32_e32 v3, v35
	v_lshlrev_b64 v[10:11], 11, v[2:3]
	v_or_b32_e32 v10, v10, v76
	v_lshl_add_u64 v[2:3], s[2:3], 0, v[10:11]
	v_lshlrev_b32_e32 v6, 16, v7
	v_and_b32_e32 v7, 0xffff0000, v7
	s_waitcnt vmcnt(3)
	v_mov_b32_e32 v2, v90
	v_mov_b32_e32 v3, v91
	v_mov_b32_e32 v4, v92
	v_mov_b32_e32 v5, v93
	v_lshlrev_b32_e32 v16, 16, v2
	v_and_b32_e32 v17, 0xffff0000, v2
	v_lshlrev_b32_e32 v2, 16, v3
	v_and_b32_e32 v3, 0xffff0000, v3
	v_lshlrev_b32_e32 v18, 16, v4
	v_and_b32_e32 v19, 0xffff0000, v4
	v_mul_f32_e32 v0, 0xbfb8aa3b, v16
	v_mul_f32_e32 v4, 0xbfb8aa3b, v17
	v_mul_f32_e32 v8, 0xbfb8aa3b, v2
	v_mul_f32_e32 v21, 0xbfb8aa3b, v3
	v_mul_f32_e32 v22, 0xbfb8aa3b, v18
	v_mul_f32_e32 v23, 0xbfb8aa3b, v19
	v_exp_f32_e32 v0, v0
	v_exp_f32_e32 v4, v4
	v_exp_f32_e32 v8, v8
	v_exp_f32_e32 v21, v21
	v_exp_f32_e32 v22, v22
	v_exp_f32_e32 v23, v23
	v_add_f32_e32 v0, 1.0, v0
	v_add_f32_e32 v4, 1.0, v4
	v_add_f32_e32 v8, 1.0, v8
	v_add_f32_e32 v21, 1.0, v21
	v_add_f32_e32 v26, 1.0, v22
	v_add_f32_e32 v27, 1.0, v23
	v_rcp_f32_e32 v22, v0
	v_rcp_f32_e32 v23, v4
	v_rcp_f32_e32 v24, v8
	v_rcp_f32_e32 v25, v21
	v_lshlrev_b32_e32 v20, 16, v5
	v_and_b32_e32 v21, 0xffff0000, v5
	v_pk_mul_f32 v[4:5], v[22:23], v[16:17]
	v_pk_mul_f32 v[2:3], v[24:25], v[2:3]
	v_pk_mul_f32 v[4:5], v[4:5], v[12:13]
	v_mul_f32_e32 v0, 0xbfb8aa3b, v20
	v_pk_mul_f32 v[6:7], v[2:3], v[6:7]
	v_cvt_pk_bf16_f32 v2, v4, v5
	v_exp_f32_e32 v0, v0
	v_mul_f32_e32 v4, 0xbfb8aa3b, v21
	v_cvt_pk_bf16_f32 v3, v6, v7
	v_exp_f32_e32 v7, v4
	v_add_f32_e32 v0, 1.0, v0
	v_rcp_f32_e32 v6, v0
	v_rcp_f32_e32 v26, v26
	v_add_f32_e32 v0, 1.0, v7
	v_rcp_f32_e32 v27, v27
	v_rcp_f32_e32 v7, v0
	v_lshlrev_b32_e32 v8, 16, v9
	v_and_b32_e32 v9, 0xffff0000, v9
	v_pk_mul_f32 v[16:17], v[26:27], v[18:19]
	v_pk_mul_f32 v[6:7], v[6:7], v[20:21]
	v_pk_mul_f32 v[4:5], v[16:17], v[14:15]
	v_pk_mul_f32 v[6:7], v[6:7], v[8:9]
	v_cvt_pk_bf16_f32 v4, v4, v5
	v_cvt_pk_bf16_f32 v5, v6, v7
	v_lshl_add_u64 v[6:7], s[94:95], 0, v[10:11]
	global_store_dwordx4 v[6:7], v[2:5], off
	ds_read_b128 v[6:9], v41 offset:2304
	s_nop 0
	v_or_b32_e32 v2, 16, v34
	v_mov_b32_e32 v3, v35
	v_lshlrev_b64 v[10:11], 11, v[2:3]
	v_or_b32_e32 v10, v10, v76
	v_lshl_add_u64 v[2:3], s[2:3], 0, v[10:11]
	v_or_b32_e32 v34, 24, v34
	v_lshlrev_b64 v[14:15], 11, v[34:35]
	v_lshl_add_u64 v[16:17], s[94:95], 0, v[10:11]
	ds_read_b128 v[10:13], v41 offset:3456
	s_waitcnt lgkmcnt(1)
	v_lshlrev_b32_e32 v20, 16, v6
	v_and_b32_e32 v21, 0xffff0000, v6
	v_lshlrev_b32_e32 v6, 16, v7
	v_and_b32_e32 v7, 0xffff0000, v7
	v_lshlrev_b32_e32 v22, 16, v8
	v_and_b32_e32 v23, 0xffff0000, v8
	v_lshlrev_b32_e32 v8, 16, v9
	v_and_b32_e32 v9, 0xffff0000, v9
	v_or_b32_e32 v14, v14, v76
	v_lshl_add_u64 v[18:19], s[2:3], 0, v[14:15]
	v_readlane_b32 s2, v245, 25
	s_add_i32 s2, s2, s74
	s_cmpk_gt_i32 s2, 0xfff
	s_waitcnt vmcnt(3)
	v_mov_b32_e32 v2, v94
	v_mov_b32_e32 v3, v95
	v_mov_b32_e32 v4, v96
	v_mov_b32_e32 v5, v97
	v_lshlrev_b32_e32 v24, 16, v2
	v_and_b32_e32 v25, 0xffff0000, v2
	v_lshlrev_b32_e32 v2, 16, v3
	v_and_b32_e32 v3, 0xffff0000, v3
	v_lshlrev_b32_e32 v26, 16, v4
	v_and_b32_e32 v27, 0xffff0000, v4
	v_lshlrev_b32_e32 v4, 16, v5
	v_and_b32_e32 v5, 0xffff0000, v5
	v_mul_f32_e32 v0, 0xbfb8aa3b, v24
	v_mul_f32_e32 v28, 0xbfb8aa3b, v25
	v_mul_f32_e32 v29, 0xbfb8aa3b, v2
	v_mul_f32_e32 v30, 0xbfb8aa3b, v3
	v_mul_f32_e32 v31, 0xbfb8aa3b, v26
	v_mul_f32_e32 v32, 0xbfb8aa3b, v27
	v_mul_f32_e32 v33, 0xbfb8aa3b, v4
	v_mul_f32_e32 v34, 0xbfb8aa3b, v5
	v_exp_f32_e32 v0, v0
	v_exp_f32_e32 v28, v28
	v_exp_f32_e32 v29, v29
	v_exp_f32_e32 v30, v30
	v_exp_f32_e32 v31, v31
	v_exp_f32_e32 v32, v32
	v_exp_f32_e32 v33, v33
	v_exp_f32_e32 v34, v34
	v_add_f32_e32 v0, 1.0, v0
	v_add_f32_e32 v35, 1.0, v28
	v_add_f32_e32 v36, 1.0, v29
	v_add_f32_e32 v37, 1.0, v30
	v_add_f32_e32 v38, 1.0, v31
	v_add_f32_e32 v39, 1.0, v32
	v_add_f32_e32 v40, 1.0, v33
	v_add_f32_e32 v41, 1.0, v34
	v_rcp_f32_e32 v28, v0
	v_rcp_f32_e32 v29, v35
	v_rcp_f32_e32 v30, v36
	v_rcp_f32_e32 v31, v37
	v_rcp_f32_e32 v32, v38
	v_rcp_f32_e32 v33, v39
	v_rcp_f32_e32 v34, v40
	v_rcp_f32_e32 v35, v41
	v_pk_mul_f32 v[24:25], v[28:29], v[24:25]
	v_pk_mul_f32 v[2:3], v[30:31], v[2:3]
	v_pk_mul_f32 v[26:27], v[32:33], v[26:27]
	v_pk_mul_f32 v[4:5], v[34:35], v[4:5]
	v_pk_mul_f32 v[20:21], v[24:25], v[20:21]
	v_pk_mul_f32 v[6:7], v[2:3], v[6:7]
	v_pk_mul_f32 v[22:23], v[26:27], v[22:23]
	v_pk_mul_f32 v[8:9], v[4:5], v[8:9]
	v_cvt_pk_bf16_f32 v2, v20, v21
	v_cvt_pk_bf16_f32 v3, v6, v7
	v_cvt_pk_bf16_f32 v4, v22, v23
	v_cvt_pk_bf16_f32 v5, v8, v9
	global_store_dwordx4 v[16:17], v[2:5], off
	v_lshl_add_u64 v[6:7], s[94:95], 0, v[14:15]
	s_waitcnt lgkmcnt(0)
	v_lshlrev_b32_e32 v8, 16, v10
	v_and_b32_e32 v9, 0xffff0000, v10
	v_lshlrev_b32_e32 v10, 16, v11
	v_and_b32_e32 v11, 0xffff0000, v11
	v_lshlrev_b32_e32 v14, 16, v12
	v_and_b32_e32 v15, 0xffff0000, v12
	v_lshlrev_b32_e32 v12, 16, v13
	v_and_b32_e32 v13, 0xffff0000, v13
	s_waitcnt vmcnt(3)
	v_mov_b32_e32 v2, v98
	v_mov_b32_e32 v3, v99
	v_mov_b32_e32 v4, v100
	v_mov_b32_e32 v5, v101
	v_lshlrev_b32_e32 v16, 16, v2
	v_and_b32_e32 v17, 0xffff0000, v2
	v_lshlrev_b32_e32 v2, 16, v3
	v_and_b32_e32 v3, 0xffff0000, v3
	v_lshlrev_b32_e32 v18, 16, v4
	v_and_b32_e32 v19, 0xffff0000, v4
	v_lshlrev_b32_e32 v4, 16, v5
	v_and_b32_e32 v5, 0xffff0000, v5
	v_mul_f32_e32 v0, 0xbfb8aa3b, v16
	v_mul_f32_e32 v20, 0xbfb8aa3b, v17
	v_mul_f32_e32 v21, 0xbfb8aa3b, v2
	v_mul_f32_e32 v22, 0xbfb8aa3b, v3
	v_mul_f32_e32 v23, 0xbfb8aa3b, v18
	v_mul_f32_e32 v24, 0xbfb8aa3b, v19
	v_mul_f32_e32 v25, 0xbfb8aa3b, v4
	v_mul_f32_e32 v26, 0xbfb8aa3b, v5
	v_exp_f32_e32 v0, v0
	v_exp_f32_e32 v20, v20
	v_exp_f32_e32 v21, v21
	v_exp_f32_e32 v22, v22
	v_exp_f32_e32 v23, v23
	v_exp_f32_e32 v24, v24
	v_exp_f32_e32 v25, v25
	v_exp_f32_e32 v26, v26
	v_add_f32_e32 v0, 1.0, v0
	v_add_f32_e32 v27, 1.0, v20
	v_add_f32_e32 v28, 1.0, v21
	v_add_f32_e32 v29, 1.0, v22
	v_add_f32_e32 v30, 1.0, v23
	v_add_f32_e32 v31, 1.0, v24
	v_add_f32_e32 v32, 1.0, v25
	v_add_f32_e32 v33, 1.0, v26
	v_rcp_f32_e32 v20, v0
	v_rcp_f32_e32 v21, v27
	v_rcp_f32_e32 v22, v28
	v_rcp_f32_e32 v23, v29
	v_rcp_f32_e32 v24, v30
	v_rcp_f32_e32 v25, v31
	v_rcp_f32_e32 v26, v32
	v_rcp_f32_e32 v27, v33
	v_pk_mul_f32 v[16:17], v[20:21], v[16:17]
	v_pk_mul_f32 v[2:3], v[22:23], v[2:3]
	v_pk_mul_f32 v[18:19], v[24:25], v[18:19]
	v_pk_mul_f32 v[4:5], v[26:27], v[4:5]
	v_pk_mul_f32 v[8:9], v[16:17], v[8:9]
	v_pk_mul_f32 v[10:11], v[2:3], v[10:11]
	v_pk_mul_f32 v[14:15], v[18:19], v[14:15]
	v_pk_mul_f32 v[12:13], v[4:5], v[12:13]
	v_cvt_pk_bf16_f32 v2, v8, v9
	v_cvt_pk_bf16_f32 v3, v10, v11
	v_cvt_pk_bf16_f32 v4, v14, v15
	v_cvt_pk_bf16_f32 v5, v12, v13
	global_store_dwordx4 v[6:7], v[2:5], off
	s_barrier
	s_cbranch_scc1 .LBB0_1371

; template <int DQK, bool MASKED, int MODE, class MF>
; DI void attn_step(const bf16_t* sK, const bf16_t* sVt, const bf16x8 (&qf)[DQK / 16], f32x16& o0, f32x16& o1, float& m, float& l,
;                   float sc, const MF& mf, int lane, f32x16 (&s)[2], float invl, bool lanevalid = true) {
;   const int r = lane & 31, h = lane >> 5;
;   const int pr = kperm(r);
;   constexpr int KST = DQK + 8;
;   bf16x8 kf[2][DQK / 16];
; #pragma unroll
;   for (int sub = 0; sub < 2; ++sub)
; #pragma unroll
;     for (int ks = 0; ks < DQK / 16; ++ks) kf[sub][ks] = *(const bf16x8*)(sK + (sub * 32 + pr) * KST + ks * 16 + 8 * h);
;   __builtin_amdgcn_sched_barrier(0);
; #pragma unroll
;   for (int q = 0; q < 16; ++q) { s[0][q] = 0.f; s[1][q] = 0.f; }
; #pragma unroll
;   for (int ks = 0; ks < DQK / 16; ++ks) {
;     s[0] = MFMA(kf[0][ks], qf[ks], s[0]);
;     s[1] = MFMA(kf[1][ks], qf[ks], s[1]);
;   }
;   bf16x8 vf[2][2][2];
;   if (MODE != 1) {
; #pragma unroll
;     for (int sub = 0; sub < 2; ++sub)
; #pragma unroll
;       for (int s2 = 0; s2 < 2; ++s2) {
;         vf[sub][s2][0] = *(const bf16x8*)(sVt + r * 72 + sub * 32 + s2 * 16 + 8 * h);
;         vf[sub][s2][1] = *(const bf16x8*)(sVt + (32 + r) * 72 + sub * 32 + s2 * 16 + 8 * h);
;       }
;     __builtin_amdgcn_sched_barrier(0);
;   }
;   float mxr = -3.0e38f;
; #pragma unroll
;   for (int sub = 0; sub < 2; ++sub)
; #pragma unroll
;     for (int q = 0; q < 16; ++q) {
;       if (MASKED) { const int kk = sub * 32 + 16 * (q >> 3) + 8 * h + (q & 7); s[sub][q] = mf(kk) ? s[sub][q] : -3.0e38f; }
;       if (MODE != 2) mxr = fmaxf(mxr, s[sub][q]);
;     }
;   float alpha = 1.f;
;   if (MODE != 2) {
;     float mx = fmaxf(m, mxr * sc);
;     mx = fmaxf(mx, shx(mx, 32));
;     if (!MASKED) mx = lanevalid ? mx : m;
;     alpha = fexp2(m - mx);
;     m = mx;
;   }
;   const float moff = (!MASKED && !lanevalid) ? 1.0e30f : m;
;   float ps = 0.f;
; #pragma unroll
;   for (int sub = 0; sub < 2; ++sub)
; #pragma unroll
;     for (int q = 0; q < 16; ++q) {
;       float pv = fexp2(__builtin_fmaf(s[sub][q], sc, -moff));
;       if (MASKED && MODE != 0) pv = (s[sub][q] > -1.0e38f) ? pv : 0.f;
;       if (MODE == 2) pv *= invl;
;       s[sub][q] = pv;
;       ps += pv;
;     }
; DI void phase_attn_nsa(const Params& P, bf16_t* og, unsigned char* smem, int L, int G) {
;     ...
;         if ((selU >> j) & 1u) {
.LBB0_1349:
	s_lshr_b32 s1, s2, s0
	s_bitcmp0_b32 s1, 0
	s_cbranch_scc1 .LBB0_1355
	v_lshrrev_b32_e32 v0, s0, v183
	s_add_i32 s6, s44, 63
	s_mulk_i32 s5, 0x4800
	v_and_b32_e32 v190, 1, v0
	s_mov_b64 s[0:1], -1
	s_cmp_le_u32 s6, s46
	v_max_f32_e32 v188, v141, v141
	v_add_u32_e32 v189, s5, v153
	v_cmp_eq_u32_e32 vcc, 1, v190
	s_cbranch_scc0 .LBB0_1352
	v_add_u32_e32 v0, s5, v182
	ds_read_b128 v[34:37], v0
	ds_read_b128 v[38:41], v0 offset:32
	ds_read_b128 v[106:109], v0 offset:64
	ds_read_b128 v[110:113], v0 offset:96
	ds_read_b128 v[42:45], v0 offset:4608
	ds_read_b128 v[114:117], v0 offset:4640
	ds_read_b128 v[118:121], v0 offset:4672
	ds_read_b128 v[194:197], v0 offset:4704
	s_waitcnt lgkmcnt(7)
	v_mfma_f32_32x32x16_bf16 v[58:73], v[34:37], v[74:77], 0
	v_add3_u32 v0, v189, v175, v138
	v_add3_u32 v34, v189, v177, v138
	s_waitcnt lgkmcnt(3)
	v_mfma_f32_32x32x16_bf16 v[42:57], v[42:45], v[74:77], 0
	v_mfma_f32_32x32x16_bf16 v[58:73], v[38:41], v[78:81], v[58:73]
	s_waitcnt lgkmcnt(2)
	v_mfma_f32_32x32x16_bf16 v[42:57], v[114:117], v[78:81], v[42:57]
	v_mfma_f32_32x32x16_bf16 v[58:73], v[106:109], v[82:85], v[58:73]
	s_waitcnt lgkmcnt(1)
	v_mfma_f32_32x32x16_bf16 v[42:57], v[118:121], v[82:85], v[42:57]
	v_mfma_f32_32x32x16_bf16 v[58:73], v[110:113], v[86:89], v[58:73]
	ds_read_b128 v[198:201], v0 offset:9216
	ds_read_b128 v[126:129], v0 offset:9248
	ds_read_b128 v[130:133], v34 offset:9216
	ds_read_b128 v[122:125], v34 offset:9248
	ds_read_b128 v[118:121], v0 offset:9280
	ds_read_b128 v[110:113], v0 offset:9312
	ds_read_b128 v[114:117], v34 offset:9280
	ds_read_b128 v[106:109], v34 offset:9312
	s_waitcnt lgkmcnt(8)
	v_mfma_f32_32x32x16_bf16 v[42:57], v[194:197], v[86:89], v[42:57]
	s_nop 1
	v_max3_f32 v0, v58, s8, v59
	v_max3_f32 v0, v0, v60, v61
	v_max3_f32 v0, v0, v62, v63
	v_max3_f32 v0, v0, v64, v65
	v_max3_f32 v0, v0, v66, v67
	v_max3_f32 v0, v0, v68, v69
	v_max3_f32 v0, v0, v70, v71
	v_max3_f32 v0, v0, v72, v73
	s_nop 1
	v_max3_f32 v0, v0, v42, v43
	v_max3_f32 v0, v0, v44, v45
	v_max3_f32 v0, v0, v46, v47
	v_max3_f32 v0, v0, v48, v49
	v_max3_f32 v0, v0, v50, v51
	v_max3_f32 v0, v0, v52, v53
	v_max3_f32 v0, v0, v54, v55
	v_max3_f32 v0, v0, v56, v57
	v_mul_f32_e32 v0, 0x3e38aa3b, v0
	v_max_f32_e32 v0, v188, v0
	ds_bpermute_b32 v34, v173, v0
	s_mov_b64 s[0:1], 0
	s_waitcnt lgkmcnt(0)
	v_max_f32_e32 v34, v34, v34
	v_max_f32_e32 v34, v0, v34
	v_cndmask_b32_e64 v191, v167, -v34, vcc
	v_fmamk_f32 v35, v58, 0x3e38aa3b, v191
	v_fmamk_f32 v36, v59, 0x3e38aa3b, v191
	v_exp_f32_e32 v58, v35
	v_fmamk_f32 v37, v60, 0x3e38aa3b, v191
	v_exp_f32_e32 v59, v36
	v_exp_f32_e32 v60, v37
	v_fmamk_f32 v35, v61, 0x3e38aa3b, v191
	v_exp_f32_e32 v61, v35
	v_add_f32_e32 v36, 0, v58
	v_fmamk_f32 v35, v62, 0x3e38aa3b, v191
	v_add_f32_e32 v36, v59, v36
	v_exp_f32_e32 v62, v35
	v_fmamk_f32 v35, v63, 0x3e38aa3b, v191
	v_add_f32_e32 v36, v60, v36
	v_exp_f32_e32 v63, v35
	v_fmamk_f32 v35, v64, 0x3e38aa3b, v191
	v_exp_f32_e32 v64, v35
	v_add_f32_e32 v35, v61, v36
	v_fmamk_f32 v36, v65, 0x3e38aa3b, v191
	v_exp_f32_e32 v65, v36
	v_fmamk_f32 v36, v66, 0x3e38aa3b, v191
	v_add_f32_e32 v35, v62, v35
	v_exp_f32_e32 v203, v36
	v_fmamk_f32 v36, v67, 0x3e38aa3b, v191
	v_add_f32_e32 v35, v63, v35
	v_exp_f32_e32 v204, v36
	v_fmamk_f32 v36, v68, 0x3e38aa3b, v191
	v_add_f32_e32 v35, v64, v35
	v_exp_f32_e32 v205, v36
	v_fmamk_f32 v36, v69, 0x3e38aa3b, v191
	v_add_f32_e32 v35, v65, v35
	v_exp_f32_e32 v206, v36
	v_fmamk_f32 v36, v70, 0x3e38aa3b, v191
	v_add_f32_e32 v35, v203, v35
	v_exp_f32_e32 v207, v36
	v_fmamk_f32 v36, v71, 0x3e38aa3b, v191
	v_add_f32_e32 v35, v204, v35
	v_exp_f32_e32 v208, v36
	v_fmamk_f32 v36, v72, 0x3e38aa3b, v191
	v_add_f32_e32 v35, v205, v35
	v_exp_f32_e32 v209, v36
	v_fmamk_f32 v36, v73, 0x3e38aa3b, v191
	v_add_f32_e32 v35, v206, v35
	v_exp_f32_e32 v210, v36
	v_fmamk_f32 v36, v42, 0x3e38aa3b, v191
	v_add_f32_e32 v35, v207, v35
	v_exp_f32_e32 v211, v36
	v_fmamk_f32 v36, v43, 0x3e38aa3b, v191
	v_add_f32_e32 v35, v208, v35
	v_exp_f32_e32 v212, v36
	v_fmamk_f32 v36, v44, 0x3e38aa3b, v191
	v_add_f32_e32 v35, v209, v35
	v_exp_f32_e32 v213, v36
	v_fmamk_f32 v36, v45, 0x3e38aa3b, v191
	v_add_f32_e32 v35, v210, v35
	v_exp_f32_e32 v214, v36
	v_fmamk_f32 v36, v46, 0x3e38aa3b, v191
	v_add_f32_e32 v35, v211, v35
	v_exp_f32_e32 v215, v36
	v_fmamk_f32 v36, v47, 0x3e38aa3b, v191
	v_cndmask_b32_e32 v0, v141, v34, vcc
	v_add_f32_e32 v35, v212, v35
	v_exp_f32_e32 v216, v36
	v_fmamk_f32 v36, v48, 0x3e38aa3b, v191
	v_sub_f32_e32 v34, v141, v0
	v_add_f32_e32 v35, v213, v35
	v_exp_f32_e32 v217, v36
	v_add_f32_e32 v35, v214, v35
	v_exp_f32_e32 v202, v34
	v_add_f32_e32 v35, v215, v35
	v_add_f32_e32 v35, v216, v35
	v_add_f32_e32 v218, v217, v35
	v_fmamk_f32 v35, v49, 0x3e38aa3b, v191
	v_fmamk_f32 v34, v50, 0x3e38aa3b, v191
	v_exp_f32_e32 v219, v35
	v_exp_f32_e32 v220, v34
	v_pk_mul_f32 v[32:33], v[32:33], v[202:203] op_sel_hi:[1,0]
	v_pk_mul_f32 v[30:31], v[30:31], v[202:203] op_sel_hi:[1,0]
	v_pk_mul_f32 v[28:29], v[28:29], v[202:203] op_sel_hi:[1,0]
	v_pk_mul_f32 v[26:27], v[26:27], v[202:203] op_sel_hi:[1,0]
	v_pk_mul_f32 v[24:25], v[24:25], v[202:203] op_sel_hi:[1,0]
	v_pk_mul_f32 v[22:23], v[22:23], v[202:203] op_sel_hi:[1,0]
	v_pk_mul_f32 v[20:21], v[20:21], v[202:203] op_sel_hi:[1,0]
	v_pk_mul_f32 v[18:19], v[18:19], v[202:203] op_sel_hi:[1,0]
	v_cvt_pk_bf16_f32 v194, v58, v59
	v_cvt_pk_bf16_f32 v195, v60, v61
	v_cvt_pk_bf16_f32 v196, v62, v63
	v_cvt_pk_bf16_f32 v197, v64, v65
	v_pk_mul_f32 v[16:17], v[16:17], v[202:203] op_sel_hi:[1,0]
	v_pk_mul_f32 v[14:15], v[14:15], v[202:203] op_sel_hi:[1,0]
	v_mfma_f32_32x32x16_bf16 v[18:33], v[198:201], v[194:197], v[18:33]
; template <int DQK, bool MASKED, int MODE, class MF>
; DI void attn_step(const bf16_t* sK, const bf16_t* sVt, const bf16x8 (&qf)[DQK / 16], f32x16& o0, f32x16& o1, float& m, float& l,
;                   float sc, const MF& mf, int lane, f32x16 (&s)[2], float invl, bool lanevalid = true) {
;     ...
;     for (int ks = 0; ks < DQK / 16; ++ks) kf[sub][ks] = *(const bf16x8*)(sK + (sub * 32 + pr) * KST + ks * 16 + 8 * h);
;   __builtin_amdgcn_sched_barrier(0);
; #pragma unroll
;   for (int q = 0; q < 16; ++q) { s[0][q] = 0.f; s[1][q] = 0.f; }
; #pragma unroll
;   for (int ks = 0; ks < DQK / 16; ++ks) {
;     s[0] = MFMA(kf[0][ks], qf[ks], s[0]);
;     s[1] = MFMA(kf[1][ks], qf[ks], s[1]);
;   }
;   bf16x8 vf[2][2][2];
;   if (MODE != 1) {
; #pragma unroll
;     for (int sub = 0; sub < 2; ++sub)
; #pragma unroll
;       for (int s2 = 0; s2 < 2; ++s2) {
;         vf[sub][s2][0] = *(const bf16x8*)(sVt + r * 72 + sub * 32 + s2 * 16 + 8 * h);
;         vf[sub][s2][1] = *(const bf16x8*)(sVt + (32 + r) * 72 + sub * 32 + s2 * 16 + 8 * h);
;       }
;     __builtin_amdgcn_sched_barrier(0);
;   }
;   float mxr = -3.0e38f;
; #pragma unroll
;   for (int sub = 0; sub < 2; ++sub)
; #pragma unroll
;     for (int q = 0; q < 16; ++q) {
;       if (MASKED) { const int kk = sub * 32 + 16 * (q >> 3) + 8 * h + (q & 7); s[sub][q] = mf(kk) ? s[sub][q] : -3.0e38f; }
;       if (MODE != 2) mxr = fmaxf(mxr, s[sub][q]);
;     }
;   float alpha = 1.f;
;   if (MODE != 2) {
;     float mx = fmaxf(m, mxr * sc);
;     mx = fmaxf(mx, shx(mx, 32));
;     if (!MASKED) mx = lanevalid ? mx : m;
;     alpha = fexp2(m - mx);
;     m = mx;
;   }
;   const float moff = (!MASKED && !lanevalid) ? 1.0e30f : m;
;   float ps = 0.f;
; #pragma unroll
;   for (int sub = 0; sub < 2; ++sub)
; #pragma unroll
;     for (int q = 0; q < 16; ++q) {
;       float pv = fexp2(__builtin_fmaf(s[sub][q], sc, -moff));
;       if (MASKED && MODE != 0) pv = (s[sub][q] > -1.0e38f) ? pv : 0.f;
;       if (MODE == 2) pv *= invl;
;       s[sub][q] = pv;
;       ps += pv;
;     }
;   if (MODE != 2) {
;     ps += shx(ps, 32);
;     l = l * alpha + ps;
;   }
;   if (MODE == 1) return;
;   if (MODE == 0) {
; #pragma unroll
;     for (int q = 0; q < 16; ++q) { o0[q] *= alpha; o1[q] *= alpha; }
;   }
; #pragma unroll
;   for (int sub = 0; sub < 2; ++sub)
; #pragma unroll
;     for (int s2 = 0; s2 < 2; ++s2) {
	v_mul_f32_e64 v12, v12, v202
	v_mul_f32_e64 v13, v13, v202
	v_mul_f32_e64 v10, v10, v202
	v_mul_f32_e64 v11, v11, v202
	v_mul_f32_e64 v8, v8, v202
	v_mul_f32_e64 v9, v9, v202
	v_pk_mul_f32 v[6:7], v[6:7], v[202:203] op_sel_hi:[1,0]
	v_pk_mul_f32 v[4:5], v[4:5], v[202:203] op_sel_hi:[1,0]
	v_pk_mul_f32 v[2:3], v[2:3], v[202:203] op_sel_hi:[1,0]
	v_fmamk_f32 v51, v51, 0x3e38aa3b, v191
	v_add_f32_e32 v50, v219, v218
	v_mfma_f32_32x32x16_bf16 v[2:17], v[130:133], v[194:197], v[2:17]
	v_cvt_pk_bf16_f32 v130, v203, v204
	v_cvt_pk_bf16_f32 v131, v205, v206
	v_cvt_pk_bf16_f32 v132, v207, v208
	v_cvt_pk_bf16_f32 v133, v209, v210
	v_add_f32_e32 v50, v220, v50
	v_fmamk_f32 v55, v55, 0x3e38aa3b, v191
	v_exp_f32_e32 v55, v55
	v_mfma_f32_32x32x16_bf16 v[18:33], v[126:129], v[130:133], v[18:33]
	v_exp_f32_e32 v126, v51
	v_fmamk_f32 v51, v52, 0x3e38aa3b, v191
	v_exp_f32_e32 v127, v51
	v_fmamk_f32 v51, v53, 0x3e38aa3b, v191
	v_exp_f32_e32 v128, v51
	v_add_f32_e32 v50, v126, v50
	v_add_f32_e32 v50, v127, v50
	v_mfma_f32_32x32x16_bf16 v[2:17], v[122:125], v[130:133], v[2:17]
	v_add_f32_e32 v122, v128, v50
	v_fmamk_f32 v50, v54, 0x3e38aa3b, v191
	v_exp_f32_e32 v54, v50
	v_fmamk_f32 v56, v56, 0x3e38aa3b, v191
	v_exp_f32_e32 v56, v56
	v_fmac_f32_e32 v191, 0x3e38aa3b, v57
	v_cvt_pk_bf16_f32 v50, v211, v212
	v_cvt_pk_bf16_f32 v51, v213, v214
	v_cvt_pk_bf16_f32 v52, v215, v216
	v_cvt_pk_bf16_f32 v53, v217, v219
	v_exp_f32_e32 v57, v191
	s_nop 0
	v_mfma_f32_32x32x16_bf16 v[18:33], v[118:121], v[50:53], v[18:33]
	v_add_f32_e32 v118, v54, v122
	v_cvt_pk_bf16_f32 v54, v54, v55
	v_mfma_f32_32x32x16_bf16 v[2:17], v[114:117], v[50:53], v[2:17]
	v_add_f32_e32 v50, v55, v118
	v_add_f32_e32 v50, v56, v50
	v_add_f32_e32 v50, v57, v50
	v_cvt_pk_bf16_f32 v52, v220, v126
	v_cvt_pk_bf16_f32 v53, v127, v128
	v_cvt_pk_bf16_f32 v55, v56, v57
	s_nop 1
	v_mfma_f32_32x32x16_bf16 v[18:33], v[110:113], v[52:55], v[18:33]
	v_mfma_f32_32x32x16_bf16 v[2:17], v[106:109], v[52:55], v[2:17]
	v_fma_f32 v50, v185, v202, v50
	s_nop 11
	v_mov_b32_e32 v141, v0
	v_mov_b32_e32 v185, v50
	s_branch .LBB0_1355
.LBB0_1352:
	s_andn2_b64 vcc, exec, s[0:1]
	s_cbranch_vccnz .LBB0_1354
	v_add_u32_e32 v0, s5, v172
	s_nop 6
	ds_read_b128 v[34:37], v0
	s_nop 0
	ds_read_b128 v[66:69], v0 offset:32
	ds_read_b128 v[70:73], v0 offset:64
	ds_read_b128 v[106:109], v0 offset:96
	ds_read_b128 v[38:41], v0 offset:4608
	ds_read_b128 v[110:113], v0 offset:4640
	ds_read_b128 v[114:117], v0 offset:4672
	ds_read_b128 v[194:197], v0 offset:4704
	v_cmp_eq_u32_e32 vcc, 1, v190
	s_waitcnt lgkmcnt(7)
	v_mfma_f32_32x32x16_bf16 v[50:65], v[34:37], v[74:77], 0
	v_lshlrev_b32_e32 v0, 1, v171
	s_waitcnt lgkmcnt(3)
	v_mfma_f32_32x32x16_bf16 v[34:49], v[38:41], v[74:77], 0
	v_mfma_f32_32x32x16_bf16 v[50:65], v[66:69], v[78:81], v[50:65]
	s_waitcnt lgkmcnt(2)
	v_mfma_f32_32x32x16_bf16 v[34:49], v[110:113], v[78:81], v[34:49]
	v_mfma_f32_32x32x16_bf16 v[50:65], v[70:73], v[82:85], v[50:65]
	v_add3_u32 v70, v189, v175, v0
	v_add3_u32 v0, v189, v177, v0
	s_waitcnt lgkmcnt(1)
	v_mfma_f32_32x32x16_bf16 v[34:49], v[114:117], v[82:85], v[34:49]
	v_mfma_f32_32x32x16_bf16 v[50:65], v[106:109], v[86:89], v[50:65]
	ds_read_b128 v[66:69], v70 offset:9216
	ds_read_b128 v[126:129], v70 offset:9248
	ds_read_b128 v[130:133], v0 offset:9216
	ds_read_b128 v[122:125], v0 offset:9248
	ds_read_b128 v[118:121], v70 offset:9280
	ds_read_b128 v[110:113], v70 offset:9312
	ds_read_b128 v[114:117], v0 offset:9280
	ds_read_b128 v[106:109], v0 offset:9312
	s_waitcnt lgkmcnt(8)
	v_mfma_f32_32x32x16_bf16 v[34:49], v[194:197], v[86:89], v[34:49]
	v_add_u32_e32 v0, s44, v171
	v_cmp_le_u32_e64 s[0:1], v0, v136
	s_and_b64 s[0:1], vcc, s[0:1]
	v_add_u32_e32 v70, 2, v0
	v_cndmask_b32_e64 v50, v166, v50, s[0:1]
	v_cmp_lt_u32_e64 s[0:1], v0, v136
	s_and_b64 s[0:1], vcc, s[0:1]
	s_nop 0
	v_cndmask_b32_e64 v51, v166, v51, s[0:1]
	v_cmp_le_u32_e64 s[0:1], v70, v136
	s_and_b64 s[0:1], vcc, s[0:1]
	v_add_u32_e32 v70, 3, v0
	v_cndmask_b32_e64 v52, v166, v52, s[0:1]
	v_cmp_le_u32_e64 s[0:1], v70, v136
	s_and_b64 s[0:1], vcc, s[0:1]
	v_add_u32_e32 v70, 4, v0
	v_cndmask_b32_e64 v53, v166, v53, s[0:1]
	v_cmp_le_u32_e64 s[0:1], v70, v136
	s_and_b64 s[0:1], vcc, s[0:1]
	v_add_u32_e32 v70, 5, v0
	v_cndmask_b32_e64 v54, v166, v54, s[0:1]
	v_cmp_le_u32_e64 s[0:1], v70, v136
	s_and_b64 s[0:1], vcc, s[0:1]
	v_add_u32_e32 v70, 6, v0
	v_cndmask_b32_e64 v55, v166, v55, s[0:1]
	v_cmp_le_u32_e64 s[0:1], v70, v136
	v_add_u32_e32 v70, s44, v139
	s_and_b64 s[0:1], vcc, s[0:1]
	v_or_b32_e32 v71, 7, v70
	v_cndmask_b32_e64 v56, v166, v56, s[0:1]
	v_cmp_le_u32_e64 s[0:1], v71, v136
	s_and_b64 s[0:1], vcc, s[0:1]
	v_add_u32_e32 v71, 16, v0
	v_cndmask_b32_e64 v57, v166, v57, s[0:1]
	v_cmp_le_u32_e64 s[0:1], v71, v136
	s_and_b64 s[0:1], vcc, s[0:1]
	v_add_u32_e32 v71, 17, v0
	v_cndmask_b32_e64 v58, v166, v58, s[0:1]
	v_cmp_le_u32_e64 s[0:1], v71, v136
	s_and_b64 s[0:1], vcc, s[0:1]
	v_add_u32_e32 v71, 18, v0
	v_cndmask_b32_e64 v59, v166, v59, s[0:1]
	v_cmp_le_u32_e64 s[0:1], v71, v136
	s_and_b64 s[0:1], vcc, s[0:1]
	v_add_u32_e32 v71, 19, v0
	v_cndmask_b32_e64 v60, v166, v60, s[0:1]
	v_cmp_le_u32_e64 s[0:1], v71, v136
	s_and_b64 s[0:1], vcc, s[0:1]
	v_add_u32_e32 v71, 20, v0
	v_cndmask_b32_e64 v61, v166, v61, s[0:1]
	v_cmp_le_u32_e64 s[0:1], v71, v136
	s_and_b64 s[0:1], vcc, s[0:1]
	v_add_u32_e32 v71, 21, v0
	v_cndmask_b32_e64 v62, v166, v62, s[0:1]
	v_cmp_le_u32_e64 s[0:1], v71, v136
	s_and_b64 s[0:1], vcc, s[0:1]
	v_add_u32_e32 v71, 22, v0
	v_cndmask_b32_e64 v63, v166, v63, s[0:1]
	v_cmp_le_u32_e64 s[0:1], v71, v136
	s_and_b64 s[0:1], vcc, s[0:1]
	v_or_b32_e32 v71, 23, v70
	v_cndmask_b32_e64 v64, v166, v64, s[0:1]
; DI float shx(float v, int m) { return __shfl_xor(v, m, 64); }
; template <int DQK, bool MASKED, int MODE, class MF>
; DI void attn_step(const bf16_t* sK, const bf16_t* sVt, const bf16x8 (&qf)[DQK / 16], f32x16& o0, f32x16& o1, float& m, float& l,
;                   float sc, const MF& mf, int lane, f32x16 (&s)[2], float invl, bool lanevalid = true) {
;     ...
;       if (MASKED) { const int kk = sub * 32 + 16 * (q >> 3) + 8 * h + (q & 7); s[sub][q] = mf(kk) ? s[sub][q] : -3.0e38f; }
;       if (MODE != 2) mxr = fmaxf(mxr, s[sub][q]);
;     }
;   float alpha = 1.f;
;   if (MODE != 2) {
;     float mx = fmaxf(m, mxr * sc);
;     mx = fmaxf(mx, shx(mx, 32));
	v_cmp_le_u32_e64 s[0:1], v71, v136
	s_and_b64 s[0:1], vcc, s[0:1]
	v_add_u32_e32 v71, 32, v0
	v_cndmask_b32_e64 v65, v166, v65, s[0:1]
	v_cmp_le_u32_e64 s[0:1], v71, v136
	s_and_b64 s[0:1], vcc, s[0:1]
	v_add_u32_e32 v71, 33, v0
	v_cndmask_b32_e64 v34, v166, v34, s[0:1]
	v_cmp_le_u32_e64 s[0:1], v71, v136
	s_and_b64 s[0:1], vcc, s[0:1]
	v_add_u32_e32 v71, 34, v0
	v_cndmask_b32_e64 v35, v166, v35, s[0:1]
	v_cmp_le_u32_e64 s[0:1], v71, v136
	s_and_b64 s[0:1], vcc, s[0:1]
	v_add_u32_e32 v71, 35, v0
	v_cndmask_b32_e64 v36, v166, v36, s[0:1]
	v_cmp_le_u32_e64 s[0:1], v71, v136
	s_and_b64 s[0:1], vcc, s[0:1]
	v_add_u32_e32 v71, 36, v0
	v_cndmask_b32_e64 v37, v166, v37, s[0:1]
	v_cmp_le_u32_e64 s[0:1], v71, v136
	s_and_b64 s[0:1], vcc, s[0:1]
	v_add_u32_e32 v71, 37, v0
	v_cndmask_b32_e64 v38, v166, v38, s[0:1]
	v_cmp_le_u32_e64 s[0:1], v71, v136
	s_and_b64 s[0:1], vcc, s[0:1]
	v_add_u32_e32 v71, 38, v0
	v_cndmask_b32_e64 v39, v166, v39, s[0:1]
	v_cmp_le_u32_e64 s[0:1], v71, v136
	s_and_b64 s[0:1], vcc, s[0:1]
	v_or_b32_e32 v71, 39, v70
	v_cndmask_b32_e64 v40, v166, v40, s[0:1]
	v_cmp_le_u32_e64 s[0:1], v71, v136
	s_and_b64 s[0:1], vcc, s[0:1]
	v_add_u32_e32 v71, 48, v0
	v_cndmask_b32_e64 v41, v166, v41, s[0:1]
	v_cmp_le_u32_e64 s[0:1], v71, v136
	s_and_b64 s[0:1], vcc, s[0:1]
	v_add_u32_e32 v71, 49, v0
	v_cndmask_b32_e64 v42, v166, v42, s[0:1]
	v_cmp_le_u32_e64 s[0:1], v71, v136
	s_and_b64 s[0:1], vcc, s[0:1]
	s_nop 0
	v_cndmask_b32_e64 v189, v166, v43, s[0:1]
	v_add_u32_e32 v43, 50, v0
	v_cmp_le_u32_e64 s[0:1], v43, v136
	s_and_b64 s[0:1], vcc, s[0:1]
	v_add_u32_e32 v43, 51, v0
	v_cndmask_b32_e64 v190, v166, v44, s[0:1]
	v_cmp_le_u32_e64 s[0:1], v43, v136
	s_and_b64 s[0:1], vcc, s[0:1]
	v_add_u32_e32 v43, 52, v0
	v_cndmask_b32_e64 v191, v166, v45, s[0:1]
	v_cmp_le_u32_e64 s[0:1], v43, v136
	s_and_b64 s[0:1], vcc, s[0:1]
	v_add_u32_e32 v43, 53, v0
	v_cndmask_b32_e64 v194, v166, v46, s[0:1]
	v_cmp_le_u32_e64 s[0:1], v43, v136
	s_and_b64 s[0:1], vcc, s[0:1]
	v_add_u32_e32 v0, 54, v0
	v_cndmask_b32_e64 v195, v166, v47, s[0:1]
	v_cmp_le_u32_e64 s[0:1], v0, v136
	s_and_b64 s[0:1], vcc, s[0:1]
	v_or_b32_e32 v0, 55, v70
	v_cndmask_b32_e64 v196, v166, v48, s[0:1]
	v_cmp_le_u32_e64 s[0:1], v0, v136
	v_max3_f32 v0, v50, s8, v51
	v_max3_f32 v0, v0, v52, v53
	v_max3_f32 v0, v0, v54, v55
	v_max3_f32 v0, v0, v56, v57
	v_max3_f32 v0, v0, v58, v59
	v_max3_f32 v0, v0, v60, v61
	v_max3_f32 v0, v0, v62, v63
	v_max3_f32 v0, v0, v64, v65
	v_max3_f32 v0, v0, v34, v35
	v_max3_f32 v0, v0, v36, v37
	v_max3_f32 v0, v0, v38, v39
	v_max3_f32 v0, v0, v40, v41
	v_max3_f32 v0, v0, v42, v189
	s_and_b64 vcc, vcc, s[0:1]
	v_max3_f32 v0, v0, v190, v191
	v_cndmask_b32_e32 v197, v166, v49, vcc
	v_max3_f32 v0, v0, v194, v195
	v_max3_f32 v0, v0, v196, v197
	v_mul_f32_e32 v0, 0x3e38aa3b, v0
	v_max_f32_e32 v0, v188, v0
	ds_bpermute_b32 v43, v173, v0
	s_waitcnt lgkmcnt(0)
; #define MFMA(a, b, c) __builtin_amdgcn_mfma_f32_32x32x16_bf16((a), (b), (c), 0, 0, 0)
; DI unsigned pack2(float a, float b) { f32x2_t v = {a, b}; bf16x2_t r = __builtin_convertvector(v, bf16x2_t); return __builtin_bit_cast(unsigned, r); }
; DI float fexp2(float x) { return __builtin_amdgcn_exp2f(x); }
; DI float shx(float v, int m) { return __shfl_xor(v, m, 64); }
; template <int DQK, bool MASKED, int MODE, class MF>
; DI void attn_step(const bf16_t* sK, const bf16_t* sVt, const bf16x8 (&qf)[DQK / 16], f32x16& o0, f32x16& o1, float& m, float& l,
;                   float sc, const MF& mf, int lane, f32x16 (&s)[2], float invl, bool lanevalid = true) {
;     ...
;   float alpha = 1.f;
;   if (MODE != 2) {
;     float mx = fmaxf(m, mxr * sc);
;     mx = fmaxf(mx, shx(mx, 32));
;     if (!MASKED) mx = lanevalid ? mx : m;
;     alpha = fexp2(m - mx);
;     m = mx;
;   }
;   const float moff = (!MASKED && !lanevalid) ? 1.0e30f : m;
;   float ps = 0.f;
; #pragma unroll
;   for (int sub = 0; sub < 2; ++sub)
; #pragma unroll
;     for (int q = 0; q < 16; ++q) {
;       float pv = fexp2(__builtin_fmaf(s[sub][q], sc, -moff));
;       if (MASKED && MODE != 0) pv = (s[sub][q] > -1.0e38f) ? pv : 0.f;
;       if (MODE == 2) pv *= invl;
;       s[sub][q] = pv;
;       ps += pv;
;     }
;   if (MODE != 2) {
;     ps += shx(ps, 32);
;     l = l * alpha + ps;
;   }
;   if (MODE == 1) return;
;   if (MODE == 0) {
; #pragma unroll
;     for (int q = 0; q < 16; ++q) { o0[q] *= alpha; o1[q] *= alpha; }
;   }
; #pragma unroll
;   for (int sub = 0; sub < 2; ++sub)
; #pragma unroll
;     for (int s2 = 0; s2 < 2; ++s2) {
;       union { bf16x8 v; unsigned u[4]; } pb;
; #pragma unroll
;       for (int e = 0; e < 4; ++e) pb.u[e] = pack2(s[sub][8 * s2 + 2 * e], s[sub][8 * s2 + 2 * e + 1]);
;       o0 = MFMA(vf[sub][s2][0], pb.v, o0);
;       o1 = MFMA(vf[sub][s2][1], pb.v, o1);
;     }
	v_max_f32_e32 v43, v43, v43
	v_max_f32_e32 v0, v0, v43
	v_fma_f32 v43, v50, s33, -v0
	v_exp_f32_e32 v50, v43
	v_fma_f32 v43, v51, s33, -v0
	v_exp_f32_e32 v51, v43
	v_fma_f32 v43, v52, s33, -v0
	v_exp_f32_e32 v70, v43
	v_fma_f32 v45, v53, s33, -v0
	v_exp_f32_e32 v53, v45
	v_fma_f32 v45, v54, s33, -v0
	v_add_f32_e32 v44, 0, v50
	v_exp_f32_e32 v54, v45
	v_fma_f32 v45, v55, s33, -v0
	v_add_f32_e32 v44, v51, v44
	v_exp_f32_e32 v55, v45
	v_fma_f32 v45, v56, s33, -v0
	v_add_f32_e32 v44, v70, v44
	v_exp_f32_e32 v56, v45
	v_fma_f32 v45, v57, s33, -v0
	v_add_f32_e32 v44, v53, v44
	v_exp_f32_e32 v57, v45
	v_fma_f32 v45, v58, s33, -v0
	v_sub_f32_e32 v43, v141, v0
	v_add_f32_e32 v44, v54, v44
	v_exp_f32_e32 v141, v45
	v_fma_f32 v45, v59, s33, -v0
	v_add_f32_e32 v44, v55, v44
	v_exp_f32_e32 v188, v45
	v_fma_f32 v45, v60, s33, -v0
	v_add_f32_e32 v44, v56, v44
	v_exp_f32_e32 v198, v45
	v_fma_f32 v45, v61, s33, -v0
	v_add_f32_e32 v44, v57, v44
	v_exp_f32_e32 v199, v45
	v_fma_f32 v45, v62, s33, -v0
	v_add_f32_e32 v44, v141, v44
	v_exp_f32_e32 v200, v45
	v_fma_f32 v45, v63, s33, -v0
	v_add_f32_e32 v44, v188, v44
	v_exp_f32_e32 v201, v45
	v_fma_f32 v45, v64, s33, -v0
	v_add_f32_e32 v44, v198, v44
	v_exp_f32_e32 v202, v45
	v_fma_f32 v45, v65, s33, -v0
	v_add_f32_e32 v44, v199, v44
	v_exp_f32_e32 v203, v45
	v_fma_f32 v34, v34, s33, -v0
	v_add_f32_e32 v44, v200, v44
	v_exp_f32_e32 v204, v34
	v_fma_f32 v34, v35, s33, -v0
	v_add_f32_e32 v44, v201, v44
	v_exp_f32_e32 v205, v34
	v_fma_f32 v34, v36, s33, -v0
	v_add_f32_e32 v44, v202, v44
	v_exp_f32_e32 v206, v34
	v_fma_f32 v35, v37, s33, -v0
	v_add_f32_e32 v34, v203, v44
	v_exp_f32_e32 v207, v35
	v_fma_f32 v35, v38, s33, -v0
	v_add_f32_e32 v34, v204, v34
	v_exp_f32_e32 v208, v35
	v_fma_f32 v35, v39, s33, -v0
	v_add_f32_e32 v34, v205, v34
	v_exp_f32_e32 v209, v35
	v_fma_f32 v35, v40, s33, -v0
	v_add_f32_e32 v34, v206, v34
	v_exp_f32_e32 v210, v35
	v_add_f32_e32 v34, v207, v34
	v_add_f32_e32 v34, v208, v34
	v_exp_f32_e32 v52, v43
	v_add_f32_e32 v34, v209, v34
	v_add_f32_e32 v211, v210, v34
	v_fma_f32 v34, v41, s33, -v0
	v_exp_f32_e32 v212, v34
	v_fma_f32 v34, v42, s33, -v0
	v_exp_f32_e32 v213, v34
	v_pk_mul_f32 v[48:49], v[32:33], v[52:53] op_sel_hi:[1,0]
	v_pk_mul_f32 v[46:47], v[30:31], v[52:53] op_sel_hi:[1,0]
	v_pk_mul_f32 v[44:45], v[28:29], v[52:53] op_sel_hi:[1,0]
	v_pk_mul_f32 v[42:43], v[26:27], v[52:53] op_sel_hi:[1,0]
	v_pk_mul_f32 v[40:41], v[24:25], v[52:53] op_sel_hi:[1,0]
	v_pk_mul_f32 v[38:39], v[22:23], v[52:53] op_sel_hi:[1,0]
	v_pk_mul_f32 v[36:37], v[20:21], v[52:53] op_sel_hi:[1,0]
	v_pk_mul_f32 v[34:35], v[18:19], v[52:53] op_sel_hi:[1,0]
	v_pk_mul_f32 v[72:73], v[16:17], v[52:53] op_sel_hi:[1,0]
	v_cvt_pk_bf16_f32 v16, v50, v51
	v_cvt_pk_bf16_f32 v17, v70, v53
	v_cvt_pk_bf16_f32 v18, v54, v55
	v_cvt_pk_bf16_f32 v19, v56, v57
	v_pk_mul_f32 v[70:71], v[14:15], v[52:53] op_sel_hi:[1,0]
	v_pk_mul_f32 v[64:65], v[8:9], v[52:53] op_sel_hi:[1,0]
	v_mfma_f32_32x32x16_bf16 v[34:49], v[66:69], v[16:19], v[34:49]
	v_mul_f32_e64 v68, v12, v52
	v_mul_f32_e64 v69, v13, v52
	v_mul_f32_e64 v66, v10, v52
	v_mul_f32_e64 v67, v11, v52
	v_mul_f32_e64 v62, v6, v52
	v_mul_f32_e64 v63, v7, v52
	v_pk_mul_f32 v[60:61], v[4:5], v[52:53] op_sel_hi:[1,0]
	v_pk_mul_f32 v[58:59], v[2:3], v[52:53] op_sel_hi:[1,0]
	v_add_f32_e32 v2, v212, v211
	v_add_f32_e32 v6, v213, v2
	v_mfma_f32_32x32x16_bf16 v[58:73], v[130:133], v[16:19], v[58:73]
	v_cvt_pk_bf16_f32 v2, v141, v188
	v_cvt_pk_bf16_f32 v3, v198, v199
	v_cvt_pk_bf16_f32 v4, v200, v201
	v_cvt_pk_bf16_f32 v5, v202, v203
	v_fma_f32 v7, v189, s33, -v0
	v_exp_f32_e32 v7, v7
	v_fma_f32 v8, v190, s33, -v0
	v_mfma_f32_32x32x16_bf16 v[34:49], v[126:129], v[2:5], v[34:49]
	v_exp_f32_e32 v8, v8
	v_fma_f32 v9, v191, s33, -v0
	v_exp_f32_e32 v9, v9
	v_fma_f32 v11, v195, s33, -v0
	v_add_f32_e32 v6, v7, v6
	v_exp_f32_e32 v11, v11
	v_fma_f32 v12, v196, s33, -v0
	v_mfma_f32_32x32x16_bf16 v[58:73], v[122:125], v[2:5], v[58:73]
	v_fma_f32 v2, v194, s33, -v0
	v_exp_f32_e32 v10, v2
	v_cvt_pk_bf16_f32 v2, v204, v205
	v_cvt_pk_bf16_f32 v3, v206, v207
	v_cvt_pk_bf16_f32 v4, v208, v209
	v_cvt_pk_bf16_f32 v5, v210, v212
	v_add_f32_e32 v6, v8, v6
	v_exp_f32_e32 v12, v12
	v_mfma_f32_32x32x16_bf16 v[34:49], v[118:121], v[2:5], v[34:49]
	v_fma_f32 v13, v197, s33, -v0
	v_add_f32_e32 v6, v9, v6
	v_exp_f32_e32 v13, v13
	v_add_f32_e32 v6, v10, v6
	v_mfma_f32_32x32x16_bf16 v[58:73], v[114:117], v[2:5], v[58:73]
	v_add_f32_e32 v2, v11, v6
	v_add_f32_e32 v2, v12, v2
	v_add_f32_e32 v6, v13, v2
	v_cvt_pk_bf16_f32 v2, v213, v7
	v_cvt_pk_bf16_f32 v3, v8, v9
	v_cvt_pk_bf16_f32 v4, v10, v11
	v_cvt_pk_bf16_f32 v5, v12, v13
	s_nop 1
	v_mfma_f32_32x32x16_bf16 v[34:49], v[110:113], v[2:5], v[34:49]
	v_mfma_f32_32x32x16_bf16 v[58:73], v[106:109], v[2:5], v[58:73]
	v_fma_f32 v50, v185, v52, v6

; DI void tot_addto(float* totL, int tid, f32x16& a, f32x16& b, float gi) {
; #pragma unroll
;   for (int k = 0; k < 4; ++k) {
;     const f32x4 v0 = *(const f32x4*)(totL + ((size_t)(k * 256 + tid)) * 4);
;     const f32x4 v1 = *(const f32x4*)(totL + ((size_t)((4 + k) * 256 + tid)) * 4);
;     a[4 * k] = v0.x + gi * a[4 * k]; a[4 * k + 1] = v0.y + gi * a[4 * k + 1]; a[4 * k + 2] = v0.z + gi * a[4 * k + 2]; a[4 * k + 3] = v0.w + gi * a[4 * k + 3];
;     b[4 * k] = v1.x + gi * b[4 * k]; b[4 * k + 1] = v1.y + gi * b[4 * k + 1]; b[4 * k + 2] = v1.z + gi * b[4 * k + 2]; b[4 * k + 3] = v1.w + gi * b[4 * k + 3];
;   }
; DI void phase_attn_nsa(const Params& P, bf16_t* og, unsigned char* smem, int L, int G) {
;     ...
;       tot_addto(totL, tid, o0, o1, g1 / l);
;       tot_store(totL, tid, o0, o1, 1.f);
;     }
;     {
;       const bf16_t* kb = big + NS_KW + (size_t)b * SEQ * 256 + g * 64;
;       const bf16_t* vb = big + NS_VWT + (size_t)((b * 4 + g) * 64) * SEQ;
;       float m = NEGF, l = 0.f; o_zero(o0, o1);
;       const int jlo = (t0 - 511 > 0 ? t0 - 511 : 0) >> 6, jhi = (t0 + 31) >> 6;
;       KVR R; kv64_fetch(R, kb, 256, vb, SEQ, jlo * 64, true, tid);
;       __syncthreads();
;       kv64_store(R, sK, sVt, tid);
;       if (jlo < jhi) kv64_fetch(R, kb, 256, vb, SEQ, jlo * 64 + 64, true, tid);
.LBB0_1357:
	ds_bpermute_b32 v247, v173, v185
	s_waitcnt lgkmcnt(0)
	v_add_f32_e32 v185, v185, v247
	v_readlane_b32 s0, v246, 48
	v_readlane_b32 s1, v246, 49
	v_lshlrev_b32_e32 v0, 1, v187
	v_mov_b32_e32 v141, v1
	v_lshl_add_u64 v[34:35], v[144:145], 1, s[0:1]
	v_readlane_b32 s0, v246, 50
	v_readlane_b32 s1, v246, 51
	v_lshl_add_u64 v[34:35], v[34:35], 0, v[0:1]
	v_div_scale_f32 v72, vcc, v178, v185, v178
	v_lshl_add_u64 v[38:39], v[142:143], 1, s[0:1]
	s_max_i32 s0, s46, 0x1ff
	s_add_i32 s2, s0, 0xfffffe01
	s_and_b32 s44, s2, 0xffffffc0
	v_or_b32_e32 v0, s44, v169
	v_lshlrev_b64 v[36:37], 9, v[0:1]
	v_or_b32_e32 v0, s44, v174
	v_lshl_add_u64 v[36:37], v[34:35], 0, v[36:37]
	v_lshlrev_b64 v[40:41], 9, v[0:1]
	v_lshl_add_u64 v[36:37], v[36:37], 0, v[140:141]
	v_lshl_add_u64 v[40:41], v[34:35], 0, v[40:41]
	v_lshlrev_b32_e32 v0, 1, v186
	v_lshl_add_u64 v[40:41], v[40:41], 0, v[140:141]
	global_load_dwordx4 v[42:45], v[36:37], off
	global_load_dwordx4 v[46:49], v[40:41], off
	v_lshl_add_u64 v[36:37], v[38:39], 0, v[0:1]
	v_lshlrev_b32_e32 v0, 1, v184
	s_lshl_b64 s[0:1], s[44:45], 1
	v_lshl_add_u64 v[38:39], v[38:39], 0, v[0:1]
	v_lshl_add_u64 v[40:41], v[36:37], 0, s[0:1]
	v_lshl_add_u64 v[54:55], v[38:39], 0, s[0:1]
	v_lshl_add_u64 v[40:41], v[40:41], 0, v[140:141]
	v_lshl_add_u64 v[58:59], v[54:55], 0, v[140:141]
	global_load_dwordx4 v[50:53], v[40:41], off
	global_load_dwordx4 v[54:57], v[58:59], off
	v_div_scale_f32 v0, s[0:1], v185, v185, v178
	v_rcp_f32_e32 v73, v0
	ds_read_b128 v[60:63], v180 offset:37376
	ds_read_b128 v[64:67], v180 offset:41472
	ds_read_b128 v[68:71], v180 offset:53760
	s_waitcnt vmcnt(7)
	ds_read_b128 v[90:93], v180 offset:57856
	s_waitcnt vmcnt(6)
	ds_read_b128 v[94:97], v180 offset:45568
	s_waitcnt vmcnt(5)
	ds_read_b128 v[98:101], v180 offset:49664
	s_waitcnt vmcnt(4)
	ds_read_b128 v[102:105], v180 offset:61952
	ds_read_b128 v[106:109], v181 offset:28672
	s_lshr_b32 s2, s2, 6
	v_fma_f32 v110, -v0, v73, 1.0
	v_fmac_f32_e32 v73, v110, v73
	v_mul_f32_e32 v110, v72, v73
	v_fma_f32 v111, -v0, v110, v72
	v_fmac_f32_e32 v110, v111, v73
	v_fma_f32 v0, -v0, v110, v72
	v_div_fmas_f32 v0, v0, v73, v110
	v_div_fixup_f32 v0, v0, v185, v178
	s_waitcnt lgkmcnt(7)
	v_pk_fma_f32 v[18:19], v[0:1], v[18:19], v[60:61] op_sel_hi:[0,1,1]
	v_pk_fma_f32 v[20:21], v[0:1], v[20:21], v[62:63] op_sel_hi:[0,1,1]
	s_cmp_lt_u32 s2, s20
	s_waitcnt lgkmcnt(5)
	v_pk_fma_f32 v[2:3], v[0:1], v[2:3], v[68:69] op_sel_hi:[0,1,1]
	v_pk_fma_f32 v[4:5], v[0:1], v[4:5], v[70:71] op_sel_hi:[0,1,1]
	v_pk_fma_f32 v[22:23], v[0:1], v[22:23], v[64:65] op_sel_hi:[0,1,1]
	v_pk_fma_f32 v[24:25], v[0:1], v[24:25], v[66:67] op_sel_hi:[0,1,1]
	s_waitcnt lgkmcnt(4)
	v_pk_fma_f32 v[6:7], v[0:1], v[6:7], v[90:91] op_sel_hi:[0,1,1]
	v_pk_fma_f32 v[8:9], v[0:1], v[8:9], v[92:93] op_sel_hi:[0,1,1]
	s_waitcnt lgkmcnt(3)
	v_pk_fma_f32 v[26:27], v[0:1], v[26:27], v[94:95] op_sel_hi:[0,1,1]
	v_pk_fma_f32 v[28:29], v[0:1], v[28:29], v[96:97] op_sel_hi:[0,1,1]
	s_waitcnt lgkmcnt(1)
	v_pk_fma_f32 v[10:11], v[0:1], v[10:11], v[102:103] op_sel_hi:[0,1,1]
	v_pk_fma_f32 v[12:13], v[0:1], v[12:13], v[104:105] op_sel_hi:[0,1,1]
	v_pk_fma_f32 v[30:31], v[0:1], v[30:31], v[98:99] op_sel_hi:[0,1,1]
	v_pk_fma_f32 v[32:33], v[0:1], v[32:33], v[100:101] op_sel_hi:[0,1,1]
	s_waitcnt lgkmcnt(0)
	v_pk_fma_f32 v[14:15], v[0:1], v[14:15], v[106:107] op_sel_hi:[0,1,1]
	v_pk_fma_f32 v[16:17], v[0:1], v[16:17], v[108:109] op_sel_hi:[0,1,1]
	ds_write_b128 v180, v[18:21] offset:37376
	ds_write_b128 v180, v[2:5] offset:53760
	ds_write_b128 v180, v[22:25] offset:41472
	ds_write_b128 v180, v[6:9] offset:57856
	ds_write_b128 v180, v[26:29] offset:45568
	ds_write_b128 v180, v[10:13] offset:61952
	ds_write_b128 v180, v[30:33] offset:49664
	ds_write_b128 v181, v[14:17] offset:28672
	s_waitcnt lgkmcnt(0)
	s_barrier
	s_waitcnt vmcnt(3)
	ds_write_b128 v170, v[42:45]
	s_waitcnt vmcnt(2)
	ds_write_b128 v170, v[46:49] offset:4608
	s_waitcnt vmcnt(1)
	ds_write_b128 v170, v[50:53] offset:9216
	s_waitcnt vmcnt(0)
	ds_write_b128 v170, v[54:57] offset:13824
	s_cbranch_scc0 .LBB0_1359
	s_add_i32 s0, s44, 64
	v_or_b32_e32 v0, s0, v169
	v_lshlrev_b64 v[2:3], 9, v[0:1]
	v_or_b32_e32 v0, s0, v174
	v_lshl_add_u64 v[2:3], v[34:35], 0, v[2:3]
	v_lshlrev_b64 v[4:5], 9, v[0:1]
	v_lshl_add_u64 v[2:3], v[2:3], 0, v[140:141]
	v_lshl_add_u64 v[4:5], v[34:35], 0, v[4:5]
	v_lshl_add_u64 v[4:5], v[4:5], 0, v[140:141]
	global_load_dwordx4 v[42:45], v[2:3], off
	global_load_dwordx4 v[46:49], v[4:5], off
	global_load_dwordx4 v[50:53], v[40:41], off offset:128
	global_load_dwordx4 v[54:57], v[58:59], off offset:128

; #define MFMA(a, b, c) __builtin_amdgcn_mfma_f32_32x32x16_bf16((a), (b), (c), 0, 0, 0)
; template <int DQK, bool MASKED, int MODE, class MF>
; DI void attn_step(const bf16_t* sK, const bf16_t* sVt, const bf16x8 (&qf)[DQK / 16], f32x16& o0, f32x16& o1, float& m, float& l,
;                   float sc, const MF& mf, int lane, f32x16 (&s)[2], float invl, bool lanevalid = true) {
;   const int r = lane & 31, h = lane >> 5;
;   const int pr = kperm(r);
;   constexpr int KST = DQK + 8;
;   bf16x8 kf[2][DQK / 16];
; #pragma unroll
;   for (int sub = 0; sub < 2; ++sub)
; #pragma unroll
;     for (int ks = 0; ks < DQK / 16; ++ks) kf[sub][ks] = *(const bf16x8*)(sK + (sub * 32 + pr) * KST + ks * 16 + 8 * h);
;   __builtin_amdgcn_sched_barrier(0);
; #pragma unroll
;   for (int q = 0; q < 16; ++q) { s[0][q] = 0.f; s[1][q] = 0.f; }
; #pragma unroll
;   for (int ks = 0; ks < DQK / 16; ++ks) {
;     s[0] = MFMA(kf[0][ks], qf[ks], s[0]);
;     s[1] = MFMA(kf[1][ks], qf[ks], s[1]);
;   }
;   bf16x8 vf[2][2][2];
;   if (MODE != 1) {
; #pragma unroll
;     for (int sub = 0; sub < 2; ++sub)
; #pragma unroll
;       for (int s2 = 0; s2 < 2; ++s2) {
;         vf[sub][s2][0] = *(const bf16x8*)(sVt + r * 72 + sub * 32 + s2 * 16 + 8 * h);
;         vf[sub][s2][1] = *(const bf16x8*)(sVt + (32 + r) * 72 + sub * 32 + s2 * 16 + 8 * h);
;       }
;     __builtin_amdgcn_sched_barrier(0);
;   }
;   float mxr = -3.0e38f;
; #pragma unroll
;   for (int sub = 0; sub < 2; ++sub)
; #pragma unroll
;     for (int q = 0; q < 16; ++q) {
;       if (MASKED) { const int kk = sub * 32 + 16 * (q >> 3) + 8 * h + (q & 7); s[sub][q] = mf(kk) ? s[sub][q] : -3.0e38f; }
; DI void phase_attn_nsa(const Params& P, bf16_t* og, unsigned char* smem, int L, int G) {
;     ...
;       for (int j = jlo; j <= jhi; ++j) {
;         const int key0 = j * 64, cb = (j - jlo) & 1;
;         __syncthreads();
;         if (j < jhi) kv64_store(R, sK + (cb ^ 1) * KVB64, sVt + (cb ^ 1) * KVB64, tid);
;         if (j + 1 < jhi) kv64_fetch(R, kb, 256, vb, SEQ, key0 + 128, true, tid);
;         __builtin_amdgcn_sched_barrier(0);
;         auto mf = [&](int kk) { const int key = key0 + kk; return key <= t && key > t - 512; };
;         if (key0 + 63 > t0 || key0 <= t0 + 31 - 512) attn_step<64, true, 0>(sK + cb * KVB64, sVt + cb * KVB64, qf, o0, o1, m, l, sc, mf, lane, s, 0.f);
.LBB0_1365:
	s_add_i32 s0, s44, 63
	s_cmp_le_u32 s0, s46
	s_cselect_b64 s[0:1], -1, 0
	s_cmp_gt_i32 s44, s3
	s_cselect_b64 s[6:7], -1, 0
	s_and_b64 s[6:7], s[0:1], s[6:7]
	s_mulk_i32 s5, 0x2400
	v_lshl_add_u32 v98, s5, 1, v153
	s_mov_b64 s[0:1], -1
	s_and_b64 vcc, exec, s[6:7]
	v_max_f32_e32 v149, v148, v148
	s_cbranch_vccnz .LBB0_1367
	v_lshl_add_u32 v0, s5, 1, v172
	ds_read_b128 v[2:5], v0
	ds_read_b128 v[34:37], v0 offset:32
	ds_read_b128 v[38:41], v0 offset:64
	ds_read_b128 v[58:61], v0 offset:96
	ds_read_b128 v[6:9], v0 offset:4608
	ds_read_b128 v[62:65], v0 offset:4640
	ds_read_b128 v[66:69], v0 offset:4672
	ds_read_b128 v[184:187], v0 offset:4704
	s_waitcnt lgkmcnt(7)
	v_mfma_f32_32x32x16_bf16 v[18:33], v[2:5], v[74:77], 0
	v_lshlrev_b32_e32 v0, 1, v171
	s_waitcnt lgkmcnt(3)
	v_mfma_f32_32x32x16_bf16 v[2:17], v[6:9], v[74:77], 0
	v_mfma_f32_32x32x16_bf16 v[18:33], v[34:37], v[78:81], v[18:33]
	v_add3_u32 v34, v98, v175, v0
	v_add3_u32 v0, v98, v177, v0
	s_waitcnt lgkmcnt(2)
	v_mfma_f32_32x32x16_bf16 v[2:17], v[62:65], v[78:81], v[2:17]
	v_mfma_f32_32x32x16_bf16 v[18:33], v[38:41], v[82:85], v[18:33]
	s_waitcnt lgkmcnt(1)
	v_mfma_f32_32x32x16_bf16 v[2:17], v[66:69], v[82:85], v[2:17]
	v_mfma_f32_32x32x16_bf16 v[18:33], v[58:61], v[86:89], v[18:33]
	ds_read_b128 v[94:97], v34 offset:9216
	ds_read_b128 v[70:73], v34 offset:9248
	ds_read_b128 v[90:93], v0 offset:9216
	ds_read_b128 v[66:69], v0 offset:9248
	ds_read_b128 v[62:65], v34 offset:9280
	ds_read_b128 v[38:41], v34 offset:9312
	ds_read_b128 v[58:61], v0 offset:9280
	ds_read_b128 v[34:37], v0 offset:9312
	s_waitcnt lgkmcnt(8)
	v_mfma_f32_32x32x16_bf16 v[2:17], v[184:187], v[86:89], v[2:17]
	v_add_u32_e32 v0, s44, v171
	v_cmp_le_u32_e32 vcc, v0, v136
	v_cmp_gt_i32_e64 s[0:1], v0, v146
	s_and_b64 vcc, vcc, s[0:1]
	v_cndmask_b32_e32 v18, v166, v18, vcc
	v_cmp_lt_u32_e32 vcc, v0, v136
	v_cmp_ge_i32_e64 s[0:1], v0, v146
	s_and_b64 vcc, vcc, s[0:1]
	v_add_u32_e32 v99, 2, v0
	v_cndmask_b32_e32 v19, v166, v19, vcc
	v_cmp_le_u32_e32 vcc, v99, v136
	v_cmp_gt_i32_e64 s[0:1], v99, v146
	s_and_b64 vcc, vcc, s[0:1]
	v_add_u32_e32 v99, 3, v0
	v_cndmask_b32_e32 v20, v166, v20, vcc
	v_cmp_le_u32_e32 vcc, v99, v136
	v_cmp_gt_i32_e64 s[0:1], v99, v146
	s_and_b64 vcc, vcc, s[0:1]
	v_add_u32_e32 v99, 4, v0
	v_cndmask_b32_e32 v21, v166, v21, vcc
	v_cmp_le_u32_e32 vcc, v99, v136
	v_cmp_gt_i32_e64 s[0:1], v99, v146
	s_and_b64 vcc, vcc, s[0:1]
	v_add_u32_e32 v99, 5, v0
	v_cndmask_b32_e32 v22, v166, v22, vcc
	v_cmp_le_u32_e32 vcc, v99, v136
	v_cmp_gt_i32_e64 s[0:1], v99, v146
	s_and_b64 vcc, vcc, s[0:1]
	v_add_u32_e32 v99, 6, v0
	v_cndmask_b32_e32 v23, v166, v23, vcc
	v_cmp_le_u32_e32 vcc, v99, v136
	v_cmp_gt_i32_e64 s[0:1], v99, v146
	v_add_u32_e32 v99, s44, v139
	s_and_b64 vcc, vcc, s[0:1]
	v_or_b32_e32 v100, 7, v99
	v_cndmask_b32_e32 v24, v166, v24, vcc
	v_cmp_le_u32_e32 vcc, v100, v136
	v_cmp_gt_i32_e64 s[0:1], v100, v146
	s_and_b64 vcc, vcc, s[0:1]
	v_add_u32_e32 v100, 16, v0
	v_cndmask_b32_e32 v25, v166, v25, vcc
	v_cmp_le_u32_e32 vcc, v100, v136
	v_cmp_gt_i32_e64 s[0:1], v100, v146
	s_and_b64 vcc, vcc, s[0:1]
	v_add_u32_e32 v100, 17, v0
	v_cndmask_b32_e32 v26, v166, v26, vcc
	v_cmp_le_u32_e32 vcc, v100, v136
	v_cmp_gt_i32_e64 s[0:1], v100, v146
	s_and_b64 vcc, vcc, s[0:1]
	v_add_u32_e32 v100, 18, v0
	v_cndmask_b32_e32 v27, v166, v27, vcc
	v_cmp_le_u32_e32 vcc, v100, v136
	v_cmp_gt_i32_e64 s[0:1], v100, v146
	s_and_b64 vcc, vcc, s[0:1]
	v_add_u32_e32 v100, 19, v0
	v_cndmask_b32_e32 v28, v166, v28, vcc
	v_cmp_le_u32_e32 vcc, v100, v136
	v_cmp_gt_i32_e64 s[0:1], v100, v146
	s_and_b64 vcc, vcc, s[0:1]
	v_add_u32_e32 v100, 20, v0
	v_cndmask_b32_e32 v29, v166, v29, vcc
	v_cmp_le_u32_e32 vcc, v100, v136
	v_cmp_gt_i32_e64 s[0:1], v100, v146
	s_and_b64 vcc, vcc, s[0:1]
	v_add_u32_e32 v100, 21, v0
	v_cndmask_b32_e32 v30, v166, v30, vcc
	v_cmp_le_u32_e32 vcc, v100, v136
	v_cmp_gt_i32_e64 s[0:1], v100, v146
	s_and_b64 vcc, vcc, s[0:1]
	v_add_u32_e32 v100, 22, v0
	v_cndmask_b32_e32 v31, v166, v31, vcc
	v_cmp_le_u32_e32 vcc, v100, v136
	v_cmp_gt_i32_e64 s[0:1], v100, v146
	s_and_b64 vcc, vcc, s[0:1]
	v_or_b32_e32 v100, 23, v99
	v_cndmask_b32_e32 v32, v166, v32, vcc
	v_cmp_le_u32_e32 vcc, v100, v136
	v_cmp_gt_i32_e64 s[0:1], v100, v146
	s_and_b64 vcc, vcc, s[0:1]
	v_add_u32_e32 v100, 32, v0
	v_cndmask_b32_e32 v33, v166, v33, vcc
	v_cmp_le_u32_e32 vcc, v100, v136
	v_cmp_gt_i32_e64 s[0:1], v100, v146
	s_and_b64 vcc, vcc, s[0:1]
	v_add_u32_e32 v100, 33, v0
	v_cndmask_b32_e32 v2, v166, v2, vcc
	v_cmp_le_u32_e32 vcc, v100, v136
	v_cmp_gt_i32_e64 s[0:1], v100, v146
	s_and_b64 vcc, vcc, s[0:1]
	v_add_u32_e32 v100, 34, v0
	v_cndmask_b32_e32 v3, v166, v3, vcc
	v_cmp_le_u32_e32 vcc, v100, v136
	v_cmp_gt_i32_e64 s[0:1], v100, v146
	s_and_b64 vcc, vcc, s[0:1]
	v_add_u32_e32 v100, 35, v0
	v_cndmask_b32_e32 v4, v166, v4, vcc
	v_cmp_le_u32_e32 vcc, v100, v136
	v_cmp_gt_i32_e64 s[0:1], v100, v146
	s_and_b64 vcc, vcc, s[0:1]
	v_add_u32_e32 v100, 36, v0
	v_cndmask_b32_e32 v5, v166, v5, vcc
	v_cmp_le_u32_e32 vcc, v100, v136
	v_cmp_gt_i32_e64 s[0:1], v100, v146
	s_and_b64 vcc, vcc, s[0:1]
	v_add_u32_e32 v100, 37, v0
	v_cndmask_b32_e32 v6, v166, v6, vcc
	v_cmp_le_u32_e32 vcc, v100, v136
	v_cmp_gt_i32_e64 s[0:1], v100, v146
	s_and_b64 vcc, vcc, s[0:1]
	v_add_u32_e32 v100, 38, v0
	v_cndmask_b32_e32 v7, v166, v7, vcc
	v_cmp_le_u32_e32 vcc, v100, v136
	v_cmp_gt_i32_e64 s[0:1], v100, v146
	s_and_b64 vcc, vcc, s[0:1]
	v_or_b32_e32 v100, 39, v99
	v_cndmask_b32_e32 v8, v166, v8, vcc
	v_cmp_le_u32_e32 vcc, v100, v136
	v_cmp_gt_i32_e64 s[0:1], v100, v146
	s_and_b64 vcc, vcc, s[0:1]
	v_add_u32_e32 v100, 48, v0
	v_cndmask_b32_e32 v9, v166, v9, vcc
; #define MFMA(a, b, c) __builtin_amdgcn_mfma_f32_32x32x16_bf16((a), (b), (c), 0, 0, 0)
; DI unsigned pack2(float a, float b) { f32x2_t v = {a, b}; bf16x2_t r = __builtin_convertvector(v, bf16x2_t); return __builtin_bit_cast(unsigned, r); }
; DI float fexp2(float x) { return __builtin_amdgcn_exp2f(x); }
; DI float shx(float v, int m) { return __shfl_xor(v, m, 64); }
; template <int DQK, bool MASKED, int MODE, class MF>
; DI void attn_step(const bf16_t* sK, const bf16_t* sVt, const bf16x8 (&qf)[DQK / 16], f32x16& o0, f32x16& o1, float& m, float& l,
;                   float sc, const MF& mf, int lane, f32x16 (&s)[2], float invl, bool lanevalid = true) {
;     ...
;       if (MASKED) { const int kk = sub * 32 + 16 * (q >> 3) + 8 * h + (q & 7); s[sub][q] = mf(kk) ? s[sub][q] : -3.0e38f; }
;       if (MODE != 2) mxr = fmaxf(mxr, s[sub][q]);
;     }
;   float alpha = 1.f;
;   if (MODE != 2) {
;     float mx = fmaxf(m, mxr * sc);
;     mx = fmaxf(mx, shx(mx, 32));
;     if (!MASKED) mx = lanevalid ? mx : m;
;     alpha = fexp2(m - mx);
;     m = mx;
;   }
;   const float moff = (!MASKED && !lanevalid) ? 1.0e30f : m;
;   float ps = 0.f;
; #pragma unroll
;   for (int sub = 0; sub < 2; ++sub)
; #pragma unroll
;     for (int q = 0; q < 16; ++q) {
;       float pv = fexp2(__builtin_fmaf(s[sub][q], sc, -moff));
;       if (MASKED && MODE != 0) pv = (s[sub][q] > -1.0e38f) ? pv : 0.f;
;       if (MODE == 2) pv *= invl;
;       s[sub][q] = pv;
;       ps += pv;
;     }
;   if (MODE != 2) {
;     ps += shx(ps, 32);
;     l = l * alpha + ps;
;   }
;   if (MODE == 1) return;
;   if (MODE == 0) {
; #pragma unroll
;     for (int q = 0; q < 16; ++q) { o0[q] *= alpha; o1[q] *= alpha; }
;   }
; #pragma unroll
;   for (int sub = 0; sub < 2; ++sub)
; #pragma unroll
;     for (int s2 = 0; s2 < 2; ++s2) {
;       union { bf16x8 v; unsigned u[4]; } pb;
; #pragma unroll
;       for (int e = 0; e < 4; ++e) pb.u[e] = pack2(s[sub][8 * s2 + 2 * e], s[sub][8 * s2 + 2 * e + 1]);
;       o0 = MFMA(vf[sub][s2][0], pb.v, o0);
;       o1 = MFMA(vf[sub][s2][1], pb.v, o1);
;     }
	v_cmp_le_u32_e32 vcc, v100, v136
	v_cmp_gt_i32_e64 s[0:1], v100, v146
	s_and_b64 vcc, vcc, s[0:1]
	v_add_u32_e32 v100, 49, v0
	v_cndmask_b32_e32 v10, v166, v10, vcc
	v_cmp_le_u32_e32 vcc, v100, v136
	v_cmp_gt_i32_e64 s[0:1], v100, v146
	s_and_b64 vcc, vcc, s[0:1]
	v_cndmask_b32_e32 v101, v166, v11, vcc
	v_add_u32_e32 v11, 50, v0
	v_cmp_le_u32_e32 vcc, v11, v136
	v_cmp_gt_i32_e64 s[0:1], v11, v146
	s_and_b64 vcc, vcc, s[0:1]
	v_add_u32_e32 v11, 51, v0
	v_cndmask_b32_e32 v150, v166, v12, vcc
	v_cmp_le_u32_e32 vcc, v11, v136
	v_cmp_gt_i32_e64 s[0:1], v11, v146
	s_and_b64 vcc, vcc, s[0:1]
	v_add_u32_e32 v11, 52, v0
	v_cndmask_b32_e32 v151, v166, v13, vcc
	v_cmp_le_u32_e32 vcc, v11, v136
	v_cmp_gt_i32_e64 s[0:1], v11, v146
	s_and_b64 vcc, vcc, s[0:1]
	v_add_u32_e32 v11, 53, v0
	v_cndmask_b32_e32 v174, v166, v14, vcc
	v_cmp_le_u32_e32 vcc, v11, v136
	v_cmp_gt_i32_e64 s[0:1], v11, v146
	s_and_b64 vcc, vcc, s[0:1]
	v_add_u32_e32 v0, 54, v0
	v_cndmask_b32_e32 v178, v166, v15, vcc
	v_cmp_le_u32_e32 vcc, v0, v136
	v_cmp_gt_i32_e64 s[0:1], v0, v146
	s_and_b64 vcc, vcc, s[0:1]
	v_or_b32_e32 v0, 55, v99
	v_cndmask_b32_e32 v183, v166, v16, vcc
	v_cmp_le_u32_e32 vcc, v0, v136
	v_cmp_gt_i32_e64 s[0:1], v0, v146
	v_max3_f32 v0, v18, s8, v19
	v_max3_f32 v0, v0, v20, v21
	v_max3_f32 v0, v0, v22, v23
	v_max3_f32 v0, v0, v24, v25
	v_max3_f32 v0, v0, v26, v27
	v_max3_f32 v0, v0, v28, v29
	v_max3_f32 v0, v0, v30, v31
	v_max3_f32 v0, v0, v32, v33
	v_max3_f32 v0, v0, v2, v3
	v_max3_f32 v0, v0, v4, v5
	v_max3_f32 v0, v0, v6, v7
	v_max3_f32 v0, v0, v8, v9
	v_max3_f32 v0, v0, v10, v101
	s_and_b64 vcc, vcc, s[0:1]
	v_max3_f32 v0, v0, v150, v151
	v_cndmask_b32_e32 v99, v166, v17, vcc
	v_max3_f32 v0, v0, v174, v178
	v_max3_f32 v0, v0, v183, v99
	v_mul_f32_e32 v0, 0x3e38aa3b, v0
	v_max_f32_e32 v0, v149, v0
	ds_bpermute_b32 v11, v173, v0
	s_mov_b64 s[0:1], 0
	s_waitcnt lgkmcnt(0)
	v_max_f32_e32 v11, v11, v11
	v_max_f32_e32 v0, v0, v11
	v_fma_f32 v11, v18, s33, -v0
	v_exp_f32_e32 v18, v11
	v_fma_f32 v11, v19, s33, -v0
	v_exp_f32_e32 v19, v11
	v_fma_f32 v11, v20, s33, -v0
	v_exp_f32_e32 v20, v11
	v_fma_f32 v13, v21, s33, -v0
	v_exp_f32_e32 v21, v13
	v_fma_f32 v13, v22, s33, -v0
	v_add_f32_e32 v12, 0, v18
	v_exp_f32_e32 v22, v13
	v_fma_f32 v13, v23, s33, -v0
	v_add_f32_e32 v12, v19, v12
	v_exp_f32_e32 v23, v13
	v_fma_f32 v13, v24, s33, -v0
	v_add_f32_e32 v12, v20, v12
	v_exp_f32_e32 v24, v13
	v_fma_f32 v13, v25, s33, -v0
	v_add_f32_e32 v12, v21, v12
	v_exp_f32_e32 v25, v13
	v_fma_f32 v13, v26, s33, -v0
	v_add_f32_e32 v12, v22, v12
	v_exp_f32_e32 v188, v13
	v_fma_f32 v13, v27, s33, -v0
	v_add_f32_e32 v12, v23, v12
	v_exp_f32_e32 v189, v13
	v_fma_f32 v13, v28, s33, -v0
	v_add_f32_e32 v12, v24, v12
	v_exp_f32_e32 v190, v13
	v_fma_f32 v13, v29, s33, -v0
	v_add_f32_e32 v12, v25, v12
	v_exp_f32_e32 v191, v13
	v_fma_f32 v13, v30, s33, -v0
	v_add_f32_e32 v12, v188, v12
	v_exp_f32_e32 v194, v13
	v_fma_f32 v13, v31, s33, -v0
	v_add_f32_e32 v12, v189, v12
	v_exp_f32_e32 v195, v13
	v_fma_f32 v13, v32, s33, -v0
	v_add_f32_e32 v12, v190, v12
	v_exp_f32_e32 v196, v13
	v_fma_f32 v13, v33, s33, -v0
	v_add_f32_e32 v12, v191, v12
	v_exp_f32_e32 v197, v13
	v_fma_f32 v2, v2, s33, -v0
	v_add_f32_e32 v12, v194, v12
	v_exp_f32_e32 v198, v2
	v_fma_f32 v2, v3, s33, -v0
	v_add_f32_e32 v12, v195, v12
	v_exp_f32_e32 v199, v2
	v_fma_f32 v2, v4, s33, -v0
	v_add_f32_e32 v12, v196, v12
	v_exp_f32_e32 v200, v2
	v_fma_f32 v3, v5, s33, -v0
	v_add_f32_e32 v2, v197, v12
	v_exp_f32_e32 v201, v3
	v_fma_f32 v3, v6, s33, -v0
	v_add_f32_e32 v2, v198, v2
	v_exp_f32_e32 v202, v3
	v_fma_f32 v3, v7, s33, -v0
	v_add_f32_e32 v2, v199, v2
	v_exp_f32_e32 v203, v3
	v_fma_f32 v3, v8, s33, -v0
	v_add_f32_e32 v2, v200, v2
	v_exp_f32_e32 v204, v3
	v_sub_f32_e32 v11, v148, v0
	v_add_f32_e32 v2, v201, v2
	v_add_f32_e32 v2, v202, v2
	v_exp_f32_e32 v100, v11
	v_add_f32_e32 v2, v203, v2
	v_add_f32_e32 v205, v204, v2
	v_fma_f32 v2, v9, s33, -v0
	v_exp_f32_e32 v206, v2
	v_fma_f32 v2, v10, s33, -v0
	v_exp_f32_e32 v207, v2
	v_pk_mul_f32 v[16:17], v[144:145], v[100:101] op_sel_hi:[1,0]
	v_pk_mul_f32 v[14:15], v[140:141], v[100:101] op_sel_hi:[1,0]
	v_pk_mul_f32 v[12:13], v[132:133], v[100:101] op_sel_hi:[1,0]
	v_pk_mul_f32 v[10:11], v[130:131], v[100:101] op_sel_hi:[1,0]
	v_pk_mul_f32 v[8:9], v[128:129], v[100:101] op_sel_hi:[1,0]
	v_pk_mul_f32 v[6:7], v[126:127], v[100:101] op_sel_hi:[1,0]
	v_pk_mul_f32 v[4:5], v[124:125], v[100:101] op_sel_hi:[1,0]
	v_pk_mul_f32 v[2:3], v[122:123], v[100:101] op_sel_hi:[1,0]
	v_pk_mul_f32 v[32:33], v[142:143], v[100:101] op_sel_hi:[1,0]
	v_cvt_pk_bf16_f32 v184, v18, v19
	v_cvt_pk_bf16_f32 v185, v20, v21
	v_cvt_pk_bf16_f32 v186, v22, v23
	v_cvt_pk_bf16_f32 v187, v24, v25
	v_pk_mul_f32 v[30:31], v[120:121], v[100:101] op_sel_hi:[1,0]
	v_pk_mul_f32 v[28:29], v[118:119], v[100:101] op_sel_hi:[1,0]
	v_pk_mul_f32 v[26:27], v[116:117], v[100:101] op_sel_hi:[1,0]
	v_pk_mul_f32 v[24:25], v[114:115], v[100:101] op_sel_hi:[1,0]
	v_pk_mul_f32 v[22:23], v[112:113], v[100:101] op_sel_hi:[1,0]
	v_pk_mul_f32 v[20:21], v[110:111], v[100:101] op_sel_hi:[1,0]
	v_pk_mul_f32 v[18:19], v[108:109], v[100:101] op_sel_hi:[1,0]
	v_mfma_f32_32x32x16_bf16 v[2:17], v[94:97], v[184:187], v[2:17]
	v_fma_f32 v95, v101, s33, -v0
	v_mfma_f32_32x32x16_bf16 v[18:33], v[90:93], v[184:187], v[18:33]
	v_add_f32_e32 v90, v206, v205
	v_add_f32_e32 v94, v207, v90
	v_cvt_pk_bf16_f32 v90, v188, v189
	v_cvt_pk_bf16_f32 v91, v190, v191
	v_cvt_pk_bf16_f32 v92, v194, v195
	v_cvt_pk_bf16_f32 v93, v196, v197
	s_nop 1
	v_mfma_f32_32x32x16_bf16 v[2:17], v[70:73], v[90:93], v[2:17]
	v_exp_f32_e32 v70, v95
	v_fma_f32 v71, v150, s33, -v0
	v_exp_f32_e32 v71, v71
	v_fma_f32 v72, v151, s33, -v0
	v_exp_f32_e32 v72, v72
	v_add_f32_e32 v73, v70, v94
	v_add_f32_e32 v73, v71, v73
	v_mfma_f32_32x32x16_bf16 v[18:33], v[66:69], v[90:93], v[18:33]
	v_fma_f32 v66, v174, s33, -v0
	v_exp_f32_e32 v90, v66
	v_cvt_pk_bf16_f32 v66, v198, v199
	v_cvt_pk_bf16_f32 v67, v200, v201
	v_cvt_pk_bf16_f32 v68, v202, v203
	v_cvt_pk_bf16_f32 v69, v204, v206
	v_add_f32_e32 v73, v72, v73
	s_nop 0
	v_mfma_f32_32x32x16_bf16 v[2:17], v[62:65], v[66:69], v[2:17]
	v_fma_f32 v63, v178, s33, -v0
	v_exp_f32_e32 v63, v63
	v_fma_f32 v64, v183, s33, -v0
	v_exp_f32_e32 v64, v64
	v_fma_f32 v65, v99, s33, -v0
	v_exp_f32_e32 v65, v65
	v_add_f32_e32 v62, v90, v73
	v_mfma_f32_32x32x16_bf16 v[18:33], v[58:61], v[66:69], v[18:33]
	v_add_f32_e32 v58, v63, v62
	v_add_f32_e32 v58, v64, v58
	v_add_f32_e32 v62, v65, v58
	v_cvt_pk_bf16_f32 v58, v207, v70
	v_cvt_pk_bf16_f32 v59, v71, v72
	v_cvt_pk_bf16_f32 v60, v90, v63
	v_cvt_pk_bf16_f32 v61, v64, v65
	s_nop 1
	v_mfma_f32_32x32x16_bf16 v[2:17], v[38:41], v[58:61], v[2:17]
	s_nop 1
	v_mfma_f32_32x32x16_bf16 v[18:33], v[34:37], v[58:61], v[18:33]
	v_fma_f32 v40, v147, v100, v62
; #define MFMA(a, b, c) __builtin_amdgcn_mfma_f32_32x32x16_bf16((a), (b), (c), 0, 0, 0)
; template <int DQK, bool MASKED, int MODE, class MF>
; DI void attn_step(const bf16_t* sK, const bf16_t* sVt, const bf16x8 (&qf)[DQK / 16], f32x16& o0, f32x16& o1, float& m, float& l,
;                   float sc, const MF& mf, int lane, f32x16 (&s)[2], float invl, bool lanevalid = true) {
;     ...
;     s[1] = MFMA(kf[1][ks], qf[ks], s[1]);
;   }
;   bf16x8 vf[2][2][2];
;   if (MODE != 1) {
; #pragma unroll
;     for (int sub = 0; sub < 2; ++sub)
; #pragma unroll
;       for (int s2 = 0; s2 < 2; ++s2) {
;         vf[sub][s2][0] = *(const bf16x8*)(sVt + r * 72 + sub * 32 + s2 * 16 + 8 * h);
;         vf[sub][s2][1] = *(const bf16x8*)(sVt + (32 + r) * 72 + sub * 32 + s2 * 16 + 8 * h);
;       }
;     __builtin_amdgcn_sched_barrier(0);
;   }
;   float mxr = -3.0e38f;
; #pragma unroll
;   for (int sub = 0; sub < 2; ++sub)
; #pragma unroll
;     for (int q = 0; q < 16; ++q) {
;       if (MASKED) { const int kk = sub * 32 + 16 * (q >> 3) + 8 * h + (q & 7); s[sub][q] = mf(kk) ? s[sub][q] : -3.0e38f; }
;       if (MODE != 2) mxr = fmaxf(mxr, s[sub][q]);
;     }
;   float alpha = 1.f;
;   if (MODE != 2) {
;     float mx = fmaxf(m, mxr * sc);
;     mx = fmaxf(mx, shx(mx, 32));
;     if (!MASKED) mx = lanevalid ? mx : m;
;     alpha = fexp2(m - mx);
;     m = mx;
;   }
;   const float moff = (!MASKED && !lanevalid) ? 1.0e30f : m;
;   float ps = 0.f;
; #pragma unroll
;   for (int sub = 0; sub < 2; ++sub)
; #pragma unroll
;     for (int q = 0; q < 16; ++q) {
;       float pv = fexp2(__builtin_fmaf(s[sub][q], sc, -moff));
;       if (MASKED && MODE != 0) pv = (s[sub][q] > -1.0e38f) ? pv : 0.f;
;       if (MODE == 2) pv *= invl;
;       s[sub][q] = pv;
;       ps += pv;
;     }
;   if (MODE != 2) {
;     ps += shx(ps, 32);
;     l = l * alpha + ps;
;   }
;   if (MODE == 1) return;
;   if (MODE == 0) {
; #pragma unroll
;     for (int q = 0; q < 16; ++q) { o0[q] *= alpha; o1[q] *= alpha; }
;   }
; #pragma unroll
;   for (int sub = 0; sub < 2; ++sub)
; #pragma unroll
;     for (int s2 = 0; s2 < 2; ++s2) {
;       union { bf16x8 v; unsigned u[4]; } pb;
; #pragma unroll
;       for (int e = 0; e < 4; ++e) pb.u[e] = pack2(s[sub][8 * s2 + 2 * e], s[sub][8 * s2 + 2 * e + 1]);
;       o0 = MFMA(vf[sub][s2][0], pb.v, o0);
;       o1 = MFMA(vf[sub][s2][1], pb.v, o1);
;     }
.LBB0_1367:
	s_andn2_b64 vcc, exec, s[0:1]
	s_cbranch_vccnz .LBB0_1369
	v_lshl_add_u32 v0, s5, 1, v182
	s_nop 3
	ds_read_b128 v[2:5], v0
	s_nop 3
	ds_read_b128 v[18:21], v0 offset:32
	ds_read_b128 v[22:25], v0 offset:64
	ds_read_b128 v[58:61], v0 offset:96
	ds_read_b128 v[26:29], v0 offset:4608
	ds_read_b128 v[62:65], v0 offset:4640
	ds_read_b128 v[66:69], v0 offset:4672
	ds_read_b128 v[184:187], v0 offset:4704
	s_waitcnt lgkmcnt(7)
	v_mfma_f32_32x32x16_bf16 v[2:17], v[2:5], v[74:77], 0
	v_add3_u32 v0, v98, v175, v138
	s_waitcnt lgkmcnt(3)
	v_mfma_f32_32x32x16_bf16 v[26:41], v[26:29], v[74:77], 0
	v_mfma_f32_32x32x16_bf16 v[2:17], v[18:21], v[78:81], v[2:17]
	s_waitcnt lgkmcnt(2)
	v_mfma_f32_32x32x16_bf16 v[26:41], v[62:65], v[78:81], v[26:41]
	v_mfma_f32_32x32x16_bf16 v[2:17], v[22:25], v[82:85], v[2:17]
	v_add3_u32 v22, v98, v177, v138
	s_waitcnt lgkmcnt(1)
	v_mfma_f32_32x32x16_bf16 v[26:41], v[66:69], v[82:85], v[26:41]
	v_mfma_f32_32x32x16_bf16 v[2:17], v[58:61], v[86:89], v[2:17]
	ds_read_b128 v[18:21], v0 offset:9216
	ds_read_b128 v[94:97], v0 offset:9248
	ds_read_b128 v[98:101], v22 offset:9216
	ds_read_b128 v[90:93], v22 offset:9248
	ds_read_b128 v[70:73], v0 offset:9280
	ds_read_b128 v[62:65], v0 offset:9312
	ds_read_b128 v[66:69], v22 offset:9280
	ds_read_b128 v[58:61], v22 offset:9312
	s_waitcnt lgkmcnt(8)
	v_mfma_f32_32x32x16_bf16 v[26:41], v[184:187], v[86:89], v[26:41]
	s_nop 1
	v_max3_f32 v0, v2, s8, v3
	v_max3_f32 v0, v0, v4, v5
	v_max3_f32 v0, v0, v6, v7
	v_max3_f32 v0, v0, v8, v9
	v_max3_f32 v0, v0, v10, v11
	v_max3_f32 v0, v0, v12, v13
	v_max3_f32 v0, v0, v14, v15
	v_max3_f32 v0, v0, v16, v17
	s_nop 1
	v_max3_f32 v0, v0, v26, v27
	v_max3_f32 v0, v0, v28, v29
	v_max3_f32 v0, v0, v30, v31
	v_max3_f32 v0, v0, v32, v33
	v_max3_f32 v0, v0, v34, v35
	v_max3_f32 v0, v0, v36, v37
	v_max3_f32 v0, v0, v38, v39
	v_max3_f32 v0, v0, v40, v41
	v_mul_f32_e32 v0, 0x3e38aa3b, v0
	v_max_f32_e32 v0, v149, v0
	ds_bpermute_b32 v22, v173, v0
	s_waitcnt lgkmcnt(0)
	v_max_f32_e32 v22, v22, v22
	v_max_f32_e32 v0, v0, v22
	v_fma_f32 v2, v2, s33, -v0
	v_fma_f32 v3, v3, s33, -v0
	v_exp_f32_e32 v23, v2
	v_fma_f32 v4, v4, s33, -v0
	v_exp_f32_e32 v24, v3
	v_fma_f32 v5, v5, s33, -v0
	v_exp_f32_e32 v25, v4
	v_exp_f32_e32 v149, v5
	v_fma_f32 v3, v6, s33, -v0
	v_add_f32_e32 v2, 0, v23
	v_exp_f32_e32 v150, v3
	v_fma_f32 v3, v7, s33, -v0
	v_add_f32_e32 v2, v24, v2
	v_exp_f32_e32 v151, v3
	v_fma_f32 v3, v8, s33, -v0
	v_add_f32_e32 v2, v25, v2
	v_exp_f32_e32 v174, v3
	v_fma_f32 v3, v9, s33, -v0
	v_add_f32_e32 v2, v149, v2
	v_exp_f32_e32 v178, v3
	v_fma_f32 v3, v10, s33, -v0
	v_add_f32_e32 v2, v150, v2
	v_exp_f32_e32 v183, v3
	v_fma_f32 v3, v11, s33, -v0
	v_add_f32_e32 v2, v151, v2
	v_exp_f32_e32 v184, v3
	v_fma_f32 v3, v12, s33, -v0
	v_add_f32_e32 v2, v174, v2
	v_exp_f32_e32 v185, v3
	v_fma_f32 v3, v13, s33, -v0
	v_add_f32_e32 v2, v178, v2
	v_exp_f32_e32 v186, v3
	v_fma_f32 v3, v14, s33, -v0
	v_add_f32_e32 v2, v183, v2
	v_exp_f32_e32 v187, v3
	v_fma_f32 v3, v15, s33, -v0
	v_add_f32_e32 v2, v184, v2
	v_exp_f32_e32 v188, v3
	v_fma_f32 v3, v16, s33, -v0
	v_add_f32_e32 v2, v185, v2
	v_exp_f32_e32 v189, v3
	v_fma_f32 v3, v17, s33, -v0
	v_add_f32_e32 v2, v186, v2
	v_exp_f32_e32 v190, v3
	v_fma_f32 v3, v26, s33, -v0
	v_add_f32_e32 v2, v187, v2
	v_exp_f32_e32 v191, v3
	v_fma_f32 v3, v27, s33, -v0
	v_add_f32_e32 v2, v188, v2
	v_exp_f32_e32 v194, v3
	v_fma_f32 v3, v28, s33, -v0
	v_add_f32_e32 v2, v189, v2
	v_exp_f32_e32 v195, v3
	v_fma_f32 v3, v29, s33, -v0
	v_add_f32_e32 v2, v190, v2
	v_exp_f32_e32 v196, v3
	v_fma_f32 v3, v30, s33, -v0
	v_add_f32_e32 v2, v191, v2
	v_exp_f32_e32 v197, v3
	v_fma_f32 v3, v31, s33, -v0
	v_add_f32_e32 v2, v194, v2
	v_exp_f32_e32 v198, v3
	v_fma_f32 v3, v32, s33, -v0
	v_add_f32_e32 v2, v195, v2
	v_exp_f32_e32 v199, v3
	v_sub_f32_e32 v22, v148, v0
	v_add_f32_e32 v2, v196, v2
	v_add_f32_e32 v2, v197, v2
	v_exp_f32_e32 v148, v22
	v_add_f32_e32 v2, v198, v2
	v_add_f32_e32 v200, v199, v2
	v_fma_f32 v2, v33, s33, -v0
	v_exp_f32_e32 v201, v2
	v_fma_f32 v2, v34, s33, -v0
	v_exp_f32_e32 v202, v2
	v_pk_mul_f32 v[16:17], v[144:145], v[148:149] op_sel_hi:[1,0]
	v_pk_mul_f32 v[14:15], v[140:141], v[148:149] op_sel_hi:[1,0]
	v_pk_mul_f32 v[12:13], v[132:133], v[148:149] op_sel_hi:[1,0]
	v_pk_mul_f32 v[10:11], v[130:131], v[148:149] op_sel_hi:[1,0]
	v_pk_mul_f32 v[8:9], v[128:129], v[148:149] op_sel_hi:[1,0]
	v_pk_mul_f32 v[6:7], v[126:127], v[148:149] op_sel_hi:[1,0]
	v_pk_mul_f32 v[4:5], v[124:125], v[148:149] op_sel_hi:[1,0]
	v_pk_mul_f32 v[2:3], v[122:123], v[148:149] op_sel_hi:[1,0]
	v_cvt_pk_bf16_f32 v122, v23, v24
	v_cvt_pk_bf16_f32 v123, v25, v149
	v_cvt_pk_bf16_f32 v124, v150, v151
	v_cvt_pk_bf16_f32 v125, v174, v178
	v_pk_mul_f32 v[32:33], v[142:143], v[148:149] op_sel_hi:[1,0]
	v_pk_mul_f32 v[30:31], v[120:121], v[148:149] op_sel_hi:[1,0]
	v_mfma_f32_32x32x16_bf16 v[2:17], v[18:21], v[122:125], v[2:17]
	v_mul_f32_e64 v28, v118, v148
	v_mul_f32_e64 v29, v119, v148
	v_mul_f32_e64 v26, v116, v148
	v_mul_f32_e64 v27, v117, v148
	v_mul_f32_e64 v24, v114, v148
	v_mul_f32_e64 v25, v115, v148
	v_pk_mul_f32 v[22:23], v[112:113], v[148:149] op_sel_hi:[1,0]
	v_pk_mul_f32 v[20:21], v[110:111], v[148:149] op_sel_hi:[1,0]
	v_pk_mul_f32 v[18:19], v[108:109], v[148:149] op_sel_hi:[1,0]
	v_fma_f32 v35, v35, s33, -v0
	v_add_f32_e32 v34, v201, v200
	v_mfma_f32_32x32x16_bf16 v[18:33], v[98:101], v[122:125], v[18:33]
	v_cvt_pk_bf16_f32 v98, v183, v184
	v_cvt_pk_bf16_f32 v99, v185, v186
	v_cvt_pk_bf16_f32 v100, v187, v188
	v_cvt_pk_bf16_f32 v101, v189, v190
	v_add_f32_e32 v34, v202, v34
	v_fma_f32 v39, v39, s33, -v0
	v_exp_f32_e32 v39, v39
	v_mfma_f32_32x32x16_bf16 v[2:17], v[94:97], v[98:101], v[2:17]
	v_exp_f32_e32 v94, v35
	v_fma_f32 v35, v36, s33, -v0
	v_exp_f32_e32 v95, v35
	v_fma_f32 v35, v37, s33, -v0
	v_exp_f32_e32 v96, v35
	v_add_f32_e32 v34, v94, v34
	v_add_f32_e32 v34, v95, v34
	v_mfma_f32_32x32x16_bf16 v[18:33], v[90:93], v[98:101], v[18:33]
	v_add_f32_e32 v90, v96, v34
	v_fma_f32 v34, v38, s33, -v0
	v_exp_f32_e32 v38, v34
	v_cvt_pk_bf16_f32 v34, v191, v194
	v_cvt_pk_bf16_f32 v35, v195, v196
	v_cvt_pk_bf16_f32 v36, v197, v198
	v_cvt_pk_bf16_f32 v37, v199, v201
	v_fma_f32 v40, v40, s33, -v0
	v_exp_f32_e32 v40, v40
	v_mfma_f32_32x32x16_bf16 v[2:17], v[70:73], v[34:37], v[2:17]
	v_fma_f32 v41, v41, s33, -v0
	v_exp_f32_e32 v41, v41
	v_add_f32_e32 v70, v38, v90
	v_mfma_f32_32x32x16_bf16 v[18:33], v[66:69], v[34:37], v[18:33]
	v_add_f32_e32 v34, v39, v70
	v_add_f32_e32 v34, v40, v34
	v_add_f32_e32 v66, v41, v34
	v_cvt_pk_bf16_f32 v34, v202, v94
	v_cvt_pk_bf16_f32 v35, v95, v96
	v_cvt_pk_bf16_f32 v36, v38, v39
	v_cvt_pk_bf16_f32 v37, v40, v41
	s_nop 1
	v_mfma_f32_32x32x16_bf16 v[2:17], v[62:65], v[34:37], v[2:17]
	v_mfma_f32_32x32x16_bf16 v[18:33], v[58:61], v[34:37], v[18:33]
	v_fma_f32 v40, v147, v148, v66
